# streaming (nt) hint on the residual base loads (P2/P8/P10 epilogues) and on the f32 residual-stream stores (P2/P8)
# baseline (speedup 1.0000x reference)
; __device__ __forceinline__ unsigned cvt_pk_bf16(float lo, float hi) { unsigned r; asm volatile("v_cvt_pk_bf16_f32 %0, %1, %2" : "=v"(r) : "v"(lo), "v"(hi)); return r; }
;     __device__ __forceinline__ void operator()(const f32x4 (&acc)[2][2][4][2], const Unit& u, int wr, int wc, int fr, int fq) const {
;     ...
;             for (int m = 0; m < 4; ++m) { const size_t r = (size_t)(row0 + ai * HALF + m * 16); const size_t off = r * ldc + col0; float ss = 0.f;
; #pragma unroll
;                 for (int bj = 0; bj < 2; ++bj) { const f32x4 b0 = *(const f32x4*)(base + off + bj * HALF), b1 = *(const f32x4*)(base + off + bj * HALF + 4);
;                     const f32x4 g0 = *(const f32x4*)(gain + col0 + bj * HALF), g1 = *(const f32x4*)(gain + col0 + bj * HALF + 4);
;                     const f32x4 v0 = b0 + acc[ai][bj][m][0] * alpha, v1 = b1 + acc[ai][bj][m][1] * alpha;
;                     *(f32x4*)(out + off + bj * HALF) = v0; *(f32x4*)(out + off + bj * HALF + 4) = v1;
;                     ss += (v0[0] * v0[0] + v0[1] * v0[1]) + (v0[2] * v0[2] + v0[3] * v0[3]) + (v1[0] * v1[0] + v1[1] * v1[1]) + (v1[2] * v1[2] + v1[3] * v1[3]);
;                     const f32x4 x0 = v0 * g0, x1 = v1 * g1;
;                     u32x4 w; w.x = cvt_pk_bf16(x0[0], x0[1]); w.y = cvt_pk_bf16(x0[2], x0[3]); w.z = cvt_pk_bf16(x1[0], x1[1]); w.w = cvt_pk_bf16(x1[2], x1[3]);
;                     *(u32x4*)(XB + off + bj * HALF) = w; }
;                 ss += __shfl_xor(ss, 16); ss += __shfl_xor(ss, 32);
;                 if (fq == 0) SSQ[r * 64 + u.pn * 4 + wc] = ss; }
.LBB0_237:
	v_lshl_add_u32 v138, s52, 8, v143
	v_lshl_or_b32 v136, s12, 8, v144
	v_ashrrev_i32_e32 v139, 31, v138
	v_ashrrev_i32_e32 v137, 31, v136
	v_lshlrev_b64 v[134:135], 12, v[138:139]
	v_lshl_add_u64 v[168:169], v[134:135], 0, v[136:137]
	v_lshlrev_b64 v[170:171], 2, v[168:169]
	v_lshl_add_u64 v[172:173], s[8:9], 0, v[170:171]
	global_load_dwordx4 v[152:155], v[172:173], off nt
	global_load_dwordx4 v[156:159], v[172:173], off offset:16 nt
	v_lshl_add_u64 v[134:135], v[136:137], 2, s[18:19]
	global_load_dwordx4 v[160:163], v[134:135], off
	global_load_dwordx4 v[164:167], v[134:135], off offset:16
	v_lshl_add_u64 v[174:175], v[168:169], 1, s[20:21]
	v_lshl_add_u64 v[176:177], s[26:27], 0, v[170:171]
	s_lshl_b32 s50, s12, 2
	s_ashr_i32 s51, s50, 31
	s_waitcnt vmcnt(3)
	v_pk_fma_f32 v[128:129], v[128:129], 0.5, v[154:155] op_sel_hi:[1,0,1]
	v_pk_fma_f32 v[126:127], v[126:127], 0.5, v[152:153] op_sel_hi:[1,0,1]
	s_waitcnt vmcnt(2)
	v_pk_fma_f32 v[154:155], v[124:125], 0.5, v[158:159] op_sel_hi:[1,0,1]
	v_pk_fma_f32 v[152:153], v[122:123], 0.5, v[156:157] op_sel_hi:[1,0,1]
	s_waitcnt vmcnt(1)
	v_pk_mul_f32 v[124:125], v[162:163], v[128:129]
	v_pk_mul_f32 v[122:123], v[160:161], v[126:127]
	global_store_dwordx4 v[176:177], v[126:129], off nt
	global_store_dwordx4 v[176:177], v[152:155], off offset:16 nt
	s_waitcnt vmcnt(2)
	v_pk_mul_f32 v[156:157], v[166:167], v[154:155]
	v_pk_mul_f32 v[158:159], v[164:165], v[152:153]
	v_cvt_pk_bf16_f32 v122, v122, v123
	v_cvt_pk_bf16_f32 v123, v124, v125
	s_nop 0
	v_cvt_pk_bf16_f32 v124, v158, v159
	v_cvt_pk_bf16_f32 v125, v156, v157
	global_store_dwordx4 v[174:175], v[122:125], off
	global_load_dwordx4 v[156:159], v[172:173], off offset:512 nt
	global_load_dwordx4 v[160:163], v[172:173], off offset:528 nt
	global_load_dwordx4 v[164:167], v[134:135], off offset:512
	global_load_dwordx4 v[168:171], v[134:135], off offset:528
	v_and_b32_e32 v123, 64, v150
	v_xor_b32_e32 v122, 16, v150
	v_add_u32_e32 v123, 64, v123
	v_xor_b32_e32 v124, 32, v150
	v_cmp_lt_i32_e32 vcc, v122, v123
	v_mul_f32_e32 v125, v129, v129
	v_fmac_f32_e32 v125, v128, v128
	v_cndmask_b32_e32 v122, v150, v122, vcc
	v_cmp_lt_i32_e32 vcc, v124, v123
	v_mul_f32_e32 v129, v155, v155
	v_fmac_f32_e32 v129, v154, v154
	v_cndmask_b32_e32 v123, v150, v124, vcc
	v_mul_f32_e32 v124, v127, v127
	v_mul_f32_e32 v127, v153, v153
	v_fmac_f32_e32 v124, v126, v126
	v_fmac_f32_e32 v127, v152, v152
	v_add_f32_e32 v124, v124, v125
	v_add_f32_e32 v124, v127, v124
	v_add_f32_e32 v126, v129, v124
	v_lshlrev_b32_e32 v122, 2, v122
	s_waitcnt vmcnt(3)
	v_pk_fma_f32 v[120:121], v[120:121], 0.5, v[158:159] op_sel_hi:[1,0,1]
	v_pk_fma_f32 v[118:119], v[118:119], 0.5, v[156:157] op_sel_hi:[1,0,1]
	s_waitcnt vmcnt(2)
	v_pk_fma_f32 v[114:115], v[114:115], 0.5, v[160:161] op_sel_hi:[1,0,1]
	v_mul_f32_e32 v127, v119, v119
	v_mul_f32_e32 v128, v121, v121
	v_pk_fma_f32 v[116:117], v[116:117], 0.5, v[162:163] op_sel_hi:[1,0,1]
	v_mul_f32_e32 v129, v115, v115
	v_fmac_f32_e32 v127, v118, v118
	v_fmac_f32_e32 v128, v120, v120
	global_store_dwordx4 v[176:177], v[118:121], off offset:512 nt
	global_store_dwordx4 v[176:177], v[114:117], off offset:528 nt
	v_mul_f32_e32 v151, v117, v117
	s_waitcnt vmcnt(3)
	v_pk_mul_f32 v[124:125], v[166:167], v[120:121]
	v_fmac_f32_e32 v129, v114, v114
	v_add_f32_e32 v120, v127, v128
	v_fmac_f32_e32 v151, v116, v116
	v_add_f32_e32 v120, v129, v120
	v_add_f32_e32 v120, v151, v120
	v_add_f32_e32 v128, v126, v120
	ds_bpermute_b32 v129, v122, v128
	s_waitcnt vmcnt(2)
	v_pk_mul_f32 v[126:127], v[170:171], v[116:117]
	v_pk_mul_f32 v[120:121], v[168:169], v[114:115]
	v_lshlrev_b32_e32 v116, 2, v123
	v_pk_mul_f32 v[118:119], v[164:165], v[118:119]
	s_waitcnt lgkmcnt(0)
	v_add_f32_e32 v114, v128, v129
	ds_bpermute_b32 v115, v116, v114
	v_cvt_pk_bf16_f32 v118, v118, v119
	v_cvt_pk_bf16_f32 v119, v124, v125
	v_cvt_pk_bf16_f32 v120, v120, v121
	v_cvt_pk_bf16_f32 v121, v126, v127
	global_store_dwordx4 v[174:175], v[118:121], off offset:256
	s_and_saveexec_b64 s[60:61], s[0:1]
	s_cbranch_execz .LBB0_239
	v_lshlrev_b64 v[118:119], 8, v[138:139]
	v_lshl_add_u64 v[118:119], s[38:39], 0, v[118:119]
	v_lshl_add_u64 v[118:119], s[50:51], 2, v[118:119]
	s_lshl_b32 s12, s87, 2
	v_lshl_add_u64 v[118:119], v[118:119], 0, s[12:13]
	s_waitcnt lgkmcnt(0)
	v_add_f32_e32 v114, v114, v115
	global_store_dword v[118:119], v114, off
; __device__ __forceinline__ unsigned cvt_pk_bf16(float lo, float hi) { unsigned r; asm volatile("v_cvt_pk_bf16_f32 %0, %1, %2" : "=v"(r) : "v"(lo), "v"(hi)); return r; }
;     __device__ __forceinline__ void operator()(const f32x4 (&acc)[2][2][4][2], const Unit& u, int wr, int wc, int fr, int fq) const {
;     ...
;             for (int m = 0; m < 4; ++m) { const size_t r = (size_t)(row0 + ai * HALF + m * 16); const size_t off = r * ldc + col0; float ss = 0.f;
; #pragma unroll
;                 for (int bj = 0; bj < 2; ++bj) { const f32x4 b0 = *(const f32x4*)(base + off + bj * HALF), b1 = *(const f32x4*)(base + off + bj * HALF + 4);
;                     const f32x4 g0 = *(const f32x4*)(gain + col0 + bj * HALF), g1 = *(const f32x4*)(gain + col0 + bj * HALF + 4);
;                     const f32x4 v0 = b0 + acc[ai][bj][m][0] * alpha, v1 = b1 + acc[ai][bj][m][1] * alpha;
;                     *(f32x4*)(out + off + bj * HALF) = v0; *(f32x4*)(out + off + bj * HALF + 4) = v1;
;                     ss += (v0[0] * v0[0] + v0[1] * v0[1]) + (v0[2] * v0[2] + v0[3] * v0[3]) + (v1[0] * v1[0] + v1[1] * v1[1]) + (v1[2] * v1[2] + v1[3] * v1[3]);
;                     const f32x4 x0 = v0 * g0, x1 = v1 * g1;
;                     u32x4 w; w.x = cvt_pk_bf16(x0[0], x0[1]); w.y = cvt_pk_bf16(x0[2], x0[3]); w.z = cvt_pk_bf16(x1[0], x1[1]); w.w = cvt_pk_bf16(x1[2], x1[3]);
;                     *(u32x4*)(XB + off + bj * HALF) = w; }
;                 ss += __shfl_xor(ss, 16); ss += __shfl_xor(ss, 32);
;                 if (fq == 0) SSQ[r * 64 + u.pn * 4 + wc] = ss; }
.LBB0_239:
	s_or_b64 exec, exec, s[60:61]
	v_or_b32_e32 v114, 16, v138
	s_waitcnt lgkmcnt(0)
	v_ashrrev_i32_e32 v115, 31, v114
	v_lshlrev_b64 v[118:119], 12, v[114:115]
	v_lshl_add_u64 v[128:129], v[118:119], 0, v[136:137]
	v_lshlrev_b64 v[160:161], 2, v[128:129]
	v_lshl_add_u64 v[162:163], s[8:9], 0, v[160:161]
	global_load_dwordx4 v[118:121], v[162:163], off nt
	global_load_dwordx4 v[124:127], v[162:163], off offset:16 nt
	global_load_dwordx4 v[152:155], v[134:135], off
	global_load_dwordx4 v[156:159], v[134:135], off offset:16
	v_lshl_add_u64 v[128:129], v[128:129], 1, s[20:21]
	v_lshl_add_u64 v[160:161], s[26:27], 0, v[160:161]
	s_waitcnt vmcnt(3)
	v_pk_fma_f32 v[112:113], v[112:113], 0.5, v[120:121] op_sel_hi:[1,0,1]
	v_pk_fma_f32 v[110:111], v[110:111], 0.5, v[118:119] op_sel_hi:[1,0,1]
	s_waitcnt vmcnt(2)
	v_pk_fma_f32 v[108:109], v[108:109], 0.5, v[126:127] op_sel_hi:[1,0,1]
	v_pk_fma_f32 v[106:107], v[106:107], 0.5, v[124:125] op_sel_hi:[1,0,1]
	s_waitcnt vmcnt(1)
	v_pk_mul_f32 v[120:121], v[154:155], v[112:113]
	v_pk_mul_f32 v[118:119], v[152:153], v[110:111]
	global_store_dwordx4 v[160:161], v[110:113], off nt
	global_store_dwordx4 v[160:161], v[106:109], off offset:16 nt
	s_waitcnt vmcnt(2)
	v_pk_mul_f32 v[124:125], v[158:159], v[108:109]
	v_pk_mul_f32 v[126:127], v[156:157], v[106:107]
	v_cvt_pk_bf16_f32 v118, v118, v119
	v_cvt_pk_bf16_f32 v119, v120, v121
	v_mul_f32_e32 v111, v111, v111
	v_cvt_pk_bf16_f32 v120, v126, v127
	v_cvt_pk_bf16_f32 v121, v124, v125
	global_store_dwordx4 v[128:129], v[118:121], off
	global_load_dwordx4 v[118:121], v[162:163], off offset:512
	s_nop 0
	global_load_dwordx4 v[124:127], v[162:163], off offset:528
	global_load_dwordx4 v[152:155], v[134:135], off offset:512
	global_load_dwordx4 v[156:159], v[134:135], off offset:528
	v_mul_f32_e32 v113, v113, v113
	v_mul_f32_e32 v107, v107, v107
	v_fmac_f32_e32 v111, v110, v110
	v_fmac_f32_e32 v113, v112, v112
	v_mul_f32_e32 v109, v109, v109
	v_fmac_f32_e32 v107, v106, v106
	v_add_f32_e32 v106, v111, v113
	v_fmac_f32_e32 v109, v108, v108
	v_add_f32_e32 v106, v107, v106
	v_add_f32_e32 v106, v109, v106
	s_waitcnt vmcnt(3)
	v_pk_fma_f32 v[104:105], v[104:105], 0.5, v[120:121] op_sel_hi:[1,0,1]
	v_pk_fma_f32 v[102:103], v[102:103], 0.5, v[118:119] op_sel_hi:[1,0,1]
	s_waitcnt vmcnt(2)
	v_pk_fma_f32 v[98:99], v[98:99], 0.5, v[124:125] op_sel_hi:[1,0,1]
	v_mul_f32_e32 v107, v103, v103
	v_mul_f32_e32 v108, v105, v105
	v_pk_fma_f32 v[100:101], v[100:101], 0.5, v[126:127] op_sel_hi:[1,0,1]
	v_mul_f32_e32 v109, v99, v99
	v_fmac_f32_e32 v107, v102, v102
	v_fmac_f32_e32 v108, v104, v104
	v_mul_f32_e32 v110, v101, v101
	v_fmac_f32_e32 v109, v98, v98
	v_add_f32_e32 v107, v107, v108
	v_fmac_f32_e32 v110, v100, v100
	v_add_f32_e32 v107, v109, v107
	v_add_f32_e32 v107, v110, v107
	v_add_f32_e32 v110, v106, v107
	ds_bpermute_b32 v111, v122, v110
	global_store_dwordx4 v[160:161], v[102:105], off offset:512 nt
	global_store_dwordx4 v[160:161], v[98:101], off offset:528 nt
	s_waitcnt vmcnt(2)
	v_pk_mul_f32 v[108:109], v[156:157], v[98:99]
	v_pk_mul_f32 v[102:103], v[152:153], v[102:103]
	v_pk_mul_f32 v[104:105], v[154:155], v[104:105]
	s_waitcnt lgkmcnt(0)
	v_add_f32_e32 v98, v110, v111
	ds_bpermute_b32 v99, v116, v98
	v_pk_mul_f32 v[106:107], v[158:159], v[100:101]
	v_cvt_pk_bf16_f32 v100, v102, v103
	v_cvt_pk_bf16_f32 v101, v104, v105
	v_cvt_pk_bf16_f32 v102, v108, v109
	s_nop 0
	v_cvt_pk_bf16_f32 v103, v106, v107
	global_store_dwordx4 v[128:129], v[100:103], off offset:256
	s_and_saveexec_b64 s[60:61], s[0:1]
	s_cbranch_execz .LBB0_241
	v_lshlrev_b64 v[100:101], 8, v[114:115]
	v_lshl_add_u64 v[100:101], s[38:39], 0, v[100:101]
	v_lshl_add_u64 v[100:101], s[50:51], 2, v[100:101]
	s_lshl_b32 s12, s87, 2
	v_lshl_add_u64 v[100:101], v[100:101], 0, s[12:13]
	s_waitcnt lgkmcnt(0)
	v_add_f32_e32 v98, v98, v99
	global_store_dword v[100:101], v98, off
.LBB0_241:
	s_or_b64 exec, exec, s[60:61]
	v_or_b32_e32 v98, 32, v138
	s_waitcnt lgkmcnt(0)
	v_ashrrev_i32_e32 v99, 31, v98
	v_lshlrev_b64 v[100:101], 12, v[98:99]
	v_lshl_add_u64 v[118:119], v[100:101], 0, v[136:137]
	v_lshlrev_b64 v[120:121], 2, v[118:119]
	v_lshl_add_u64 v[124:125], s[8:9], 0, v[120:121]
	global_load_dwordx4 v[100:103], v[124:125], off nt
	global_load_dwordx4 v[104:107], v[124:125], off offset:16 nt
	global_load_dwordx4 v[108:111], v[134:135], off
	global_load_dwordx4 v[112:115], v[134:135], off offset:16
	v_lshl_add_u64 v[118:119], v[118:119], 1, s[20:21]
	v_lshl_add_u64 v[120:121], s[26:27], 0, v[120:121]
	s_waitcnt vmcnt(3)
	v_pk_fma_f32 v[96:97], v[96:97], 0.5, v[102:103] op_sel_hi:[1,0,1]
	v_pk_fma_f32 v[94:95], v[94:95], 0.5, v[100:101] op_sel_hi:[1,0,1]
	s_waitcnt vmcnt(2)
	v_pk_fma_f32 v[92:93], v[92:93], 0.5, v[106:107] op_sel_hi:[1,0,1]
	v_pk_fma_f32 v[90:91], v[90:91], 0.5, v[104:105] op_sel_hi:[1,0,1]
	s_waitcnt vmcnt(1)
	v_pk_mul_f32 v[102:103], v[110:111], v[96:97]
	v_pk_mul_f32 v[100:101], v[108:109], v[94:95]
	global_store_dwordx4 v[120:121], v[94:97], off nt
	global_store_dwordx4 v[120:121], v[90:93], off offset:16 nt
	s_waitcnt vmcnt(2)
	v_pk_mul_f32 v[104:105], v[114:115], v[92:93]
	v_pk_mul_f32 v[106:107], v[112:113], v[90:91]
	v_cvt_pk_bf16_f32 v100, v100, v101
	v_cvt_pk_bf16_f32 v101, v102, v103
	v_mul_f32_e32 v95, v95, v95
	v_cvt_pk_bf16_f32 v102, v106, v107
	v_cvt_pk_bf16_f32 v103, v104, v105
	global_store_dwordx4 v[118:119], v[100:103], off
	global_load_dwordx4 v[100:103], v[124:125], off offset:512
	s_nop 0
	global_load_dwordx4 v[104:107], v[124:125], off offset:528
	global_load_dwordx4 v[108:111], v[134:135], off offset:512
	global_load_dwordx4 v[112:115], v[134:135], off offset:528
	v_mul_f32_e32 v97, v97, v97
	v_mul_f32_e32 v91, v91, v91
	v_fmac_f32_e32 v95, v94, v94
	v_fmac_f32_e32 v97, v96, v96
	v_mul_f32_e32 v93, v93, v93
	v_fmac_f32_e32 v91, v90, v90
	v_add_f32_e32 v90, v95, v97
	v_fmac_f32_e32 v93, v92, v92
	v_add_f32_e32 v90, v91, v90
	v_add_f32_e32 v90, v93, v90
	s_waitcnt vmcnt(3)
; __device__ __forceinline__ unsigned cvt_pk_bf16(float lo, float hi) { unsigned r; asm volatile("v_cvt_pk_bf16_f32 %0, %1, %2" : "=v"(r) : "v"(lo), "v"(hi)); return r; }
;     __device__ __forceinline__ void operator()(const f32x4 (&acc)[2][2][4][2], const Unit& u, int wr, int wc, int fr, int fq) const {
;     ...
;             for (int m = 0; m < 4; ++m) { const size_t r = (size_t)(row0 + ai * HALF + m * 16); const size_t off = r * ldc + col0; float ss = 0.f;
; #pragma unroll
;                 for (int bj = 0; bj < 2; ++bj) { const f32x4 b0 = *(const f32x4*)(base + off + bj * HALF), b1 = *(const f32x4*)(base + off + bj * HALF + 4);
;                     const f32x4 g0 = *(const f32x4*)(gain + col0 + bj * HALF), g1 = *(const f32x4*)(gain + col0 + bj * HALF + 4);
;                     const f32x4 v0 = b0 + acc[ai][bj][m][0] * alpha, v1 = b1 + acc[ai][bj][m][1] * alpha;
;                     *(f32x4*)(out + off + bj * HALF) = v0; *(f32x4*)(out + off + bj * HALF + 4) = v1;
;                     ss += (v0[0] * v0[0] + v0[1] * v0[1]) + (v0[2] * v0[2] + v0[3] * v0[3]) + (v1[0] * v1[0] + v1[1] * v1[1]) + (v1[2] * v1[2] + v1[3] * v1[3]);
;                     const f32x4 x0 = v0 * g0, x1 = v1 * g1;
;                     u32x4 w; w.x = cvt_pk_bf16(x0[0], x0[1]); w.y = cvt_pk_bf16(x0[2], x0[3]); w.z = cvt_pk_bf16(x1[0], x1[1]); w.w = cvt_pk_bf16(x1[2], x1[3]);
;                     *(u32x4*)(XB + off + bj * HALF) = w; }
;                 ss += __shfl_xor(ss, 16); ss += __shfl_xor(ss, 32);
;                 if (fq == 0) SSQ[r * 64 + u.pn * 4 + wc] = ss; }
	v_pk_fma_f32 v[88:89], v[88:89], 0.5, v[102:103] op_sel_hi:[1,0,1]
	v_pk_fma_f32 v[86:87], v[86:87], 0.5, v[100:101] op_sel_hi:[1,0,1]
	s_waitcnt vmcnt(2)
	v_pk_fma_f32 v[82:83], v[82:83], 0.5, v[104:105] op_sel_hi:[1,0,1]
	v_mul_f32_e32 v91, v87, v87
	v_mul_f32_e32 v92, v89, v89
	v_pk_fma_f32 v[84:85], v[84:85], 0.5, v[106:107] op_sel_hi:[1,0,1]
	v_mul_f32_e32 v93, v83, v83
	v_fmac_f32_e32 v91, v86, v86
	v_fmac_f32_e32 v92, v88, v88
	v_mul_f32_e32 v94, v85, v85
	v_fmac_f32_e32 v93, v82, v82
	v_add_f32_e32 v91, v91, v92
	v_fmac_f32_e32 v94, v84, v84
	v_add_f32_e32 v91, v93, v91
	v_add_f32_e32 v91, v94, v91
	v_add_f32_e32 v94, v90, v91
	ds_bpermute_b32 v95, v122, v94
	global_store_dwordx4 v[120:121], v[86:89], off offset:512 nt
	global_store_dwordx4 v[120:121], v[82:85], off offset:528 nt
	s_waitcnt vmcnt(2)
	v_pk_mul_f32 v[92:93], v[112:113], v[82:83]
	v_pk_mul_f32 v[86:87], v[108:109], v[86:87]
	v_pk_mul_f32 v[88:89], v[110:111], v[88:89]
	s_waitcnt lgkmcnt(0)
	v_add_f32_e32 v82, v94, v95
	ds_bpermute_b32 v83, v116, v82
	v_pk_mul_f32 v[90:91], v[114:115], v[84:85]
	v_cvt_pk_bf16_f32 v84, v86, v87
	v_cvt_pk_bf16_f32 v85, v88, v89
	v_cvt_pk_bf16_f32 v86, v92, v93
	s_nop 0
	v_cvt_pk_bf16_f32 v87, v90, v91
	global_store_dwordx4 v[118:119], v[84:87], off offset:256
	s_and_saveexec_b64 s[60:61], s[0:1]
	s_cbranch_execz .LBB0_243
	v_lshlrev_b64 v[84:85], 8, v[98:99]
	v_lshl_add_u64 v[84:85], s[38:39], 0, v[84:85]
	v_lshl_add_u64 v[84:85], s[50:51], 2, v[84:85]
	s_lshl_b32 s12, s87, 2
	v_lshl_add_u64 v[84:85], v[84:85], 0, s[12:13]
	s_waitcnt lgkmcnt(0)
	v_add_f32_e32 v82, v82, v83
	global_store_dword v[84:85], v82, off
.LBB0_243:
	s_or_b64 exec, exec, s[60:61]
	v_or_b32_e32 v82, 48, v138
	s_waitcnt lgkmcnt(0)
	v_ashrrev_i32_e32 v83, 31, v82
	v_lshlrev_b64 v[84:85], 12, v[82:83]
	v_lshl_add_u64 v[100:101], v[84:85], 0, v[136:137]
	v_lshlrev_b64 v[102:103], 2, v[100:101]
	v_lshl_add_u64 v[104:105], s[8:9], 0, v[102:103]
	global_load_dwordx4 v[84:87], v[104:105], off nt
	global_load_dwordx4 v[88:91], v[104:105], off offset:16 nt
	global_load_dwordx4 v[92:95], v[134:135], off
	global_load_dwordx4 v[96:99], v[134:135], off offset:16
	v_lshl_add_u64 v[100:101], v[100:101], 1, s[20:21]
	v_lshl_add_u64 v[102:103], s[26:27], 0, v[102:103]
	s_waitcnt vmcnt(3)
	v_pk_fma_f32 v[80:81], v[80:81], 0.5, v[86:87] op_sel_hi:[1,0,1]
	v_pk_fma_f32 v[78:79], v[78:79], 0.5, v[84:85] op_sel_hi:[1,0,1]
	s_waitcnt vmcnt(2)
	v_pk_fma_f32 v[76:77], v[76:77], 0.5, v[90:91] op_sel_hi:[1,0,1]
	v_pk_fma_f32 v[74:75], v[74:75], 0.5, v[88:89] op_sel_hi:[1,0,1]
	s_waitcnt vmcnt(1)
	v_pk_mul_f32 v[86:87], v[94:95], v[80:81]
	v_pk_mul_f32 v[84:85], v[92:93], v[78:79]
	global_store_dwordx4 v[102:103], v[78:81], off nt
	global_store_dwordx4 v[102:103], v[74:77], off offset:16 nt
	s_waitcnt vmcnt(2)
	v_pk_mul_f32 v[88:89], v[98:99], v[76:77]
	v_pk_mul_f32 v[90:91], v[96:97], v[74:75]
	v_cvt_pk_bf16_f32 v84, v84, v85
	v_cvt_pk_bf16_f32 v85, v86, v87
	v_mul_f32_e32 v79, v79, v79
	v_cvt_pk_bf16_f32 v86, v90, v91
	v_cvt_pk_bf16_f32 v87, v88, v89
	global_store_dwordx4 v[100:101], v[84:87], off
	global_load_dwordx4 v[84:87], v[104:105], off offset:512
	s_nop 0
	global_load_dwordx4 v[88:91], v[104:105], off offset:528
	global_load_dwordx4 v[92:95], v[134:135], off offset:512
	global_load_dwordx4 v[96:99], v[134:135], off offset:528
	v_mul_f32_e32 v81, v81, v81
	v_mul_f32_e32 v75, v75, v75
	v_fmac_f32_e32 v79, v78, v78
	v_fmac_f32_e32 v81, v80, v80
	v_mul_f32_e32 v77, v77, v77
	v_fmac_f32_e32 v75, v74, v74
	v_add_f32_e32 v74, v79, v81
	v_fmac_f32_e32 v77, v76, v76
	v_add_f32_e32 v74, v75, v74
	v_add_f32_e32 v74, v77, v74
	s_waitcnt vmcnt(3)
	v_pk_fma_f32 v[72:73], v[72:73], 0.5, v[86:87] op_sel_hi:[1,0,1]
	v_pk_fma_f32 v[70:71], v[70:71], 0.5, v[84:85] op_sel_hi:[1,0,1]
	s_waitcnt vmcnt(2)
	v_pk_fma_f32 v[66:67], v[66:67], 0.5, v[88:89] op_sel_hi:[1,0,1]
	v_mul_f32_e32 v75, v71, v71
	v_mul_f32_e32 v76, v73, v73
	v_pk_fma_f32 v[68:69], v[68:69], 0.5, v[90:91] op_sel_hi:[1,0,1]
	v_mul_f32_e32 v77, v67, v67
	v_fmac_f32_e32 v75, v70, v70
	v_fmac_f32_e32 v76, v72, v72
	v_mul_f32_e32 v78, v69, v69
	v_fmac_f32_e32 v77, v66, v66
	v_add_f32_e32 v75, v75, v76
	v_fmac_f32_e32 v78, v68, v68
	v_add_f32_e32 v75, v77, v75
	v_add_f32_e32 v75, v78, v75
	v_add_f32_e32 v78, v74, v75
	ds_bpermute_b32 v79, v122, v78
	global_store_dwordx4 v[102:103], v[70:73], off offset:512 nt
	global_store_dwordx4 v[102:103], v[66:69], off offset:528 nt
	s_waitcnt vmcnt(2)
	v_pk_mul_f32 v[76:77], v[96:97], v[66:67]
	v_pk_mul_f32 v[70:71], v[92:93], v[70:71]
	v_pk_mul_f32 v[72:73], v[94:95], v[72:73]
	s_waitcnt lgkmcnt(0)
	v_add_f32_e32 v66, v78, v79
	ds_bpermute_b32 v67, v116, v66
	v_pk_mul_f32 v[74:75], v[98:99], v[68:69]
	v_cvt_pk_bf16_f32 v68, v70, v71
	v_cvt_pk_bf16_f32 v69, v72, v73
	v_cvt_pk_bf16_f32 v70, v76, v77
	s_nop 0
	v_cvt_pk_bf16_f32 v71, v74, v75
	global_store_dwordx4 v[100:101], v[68:71], off offset:256
	s_and_saveexec_b64 s[60:61], s[0:1]
	s_cbranch_execz .LBB0_245
	v_lshlrev_b64 v[68:69], 8, v[82:83]
	v_lshl_add_u64 v[68:69], s[38:39], 0, v[68:69]
	v_lshl_add_u64 v[68:69], s[50:51], 2, v[68:69]
	s_lshl_b32 s12, s87, 2
	v_lshl_add_u64 v[68:69], v[68:69], 0, s[12:13]
	s_waitcnt lgkmcnt(0)
	v_add_f32_e32 v66, v66, v67
	global_store_dword v[68:69], v66, off
; __device__ __forceinline__ unsigned cvt_pk_bf16(float lo, float hi) { unsigned r; asm volatile("v_cvt_pk_bf16_f32 %0, %1, %2" : "=v"(r) : "v"(lo), "v"(hi)); return r; }
;     __device__ __forceinline__ void operator()(const f32x4 (&acc)[2][2][4][2], const Unit& u, int wr, int wc, int fr, int fq) const {
;     ...
;             for (int m = 0; m < 4; ++m) { const size_t r = (size_t)(row0 + ai * HALF + m * 16); const size_t off = r * ldc + col0; float ss = 0.f;
; #pragma unroll
;                 for (int bj = 0; bj < 2; ++bj) { const f32x4 b0 = *(const f32x4*)(base + off + bj * HALF), b1 = *(const f32x4*)(base + off + bj * HALF + 4);
;                     const f32x4 g0 = *(const f32x4*)(gain + col0 + bj * HALF), g1 = *(const f32x4*)(gain + col0 + bj * HALF + 4);
;                     const f32x4 v0 = b0 + acc[ai][bj][m][0] * alpha, v1 = b1 + acc[ai][bj][m][1] * alpha;
;                     *(f32x4*)(out + off + bj * HALF) = v0; *(f32x4*)(out + off + bj * HALF + 4) = v1;
;                     ss += (v0[0] * v0[0] + v0[1] * v0[1]) + (v0[2] * v0[2] + v0[3] * v0[3]) + (v1[0] * v1[0] + v1[1] * v1[1]) + (v1[2] * v1[2] + v1[3] * v1[3]);
;                     const f32x4 x0 = v0 * g0, x1 = v1 * g1;
;                     u32x4 w; w.x = cvt_pk_bf16(x0[0], x0[1]); w.y = cvt_pk_bf16(x0[2], x0[3]); w.z = cvt_pk_bf16(x1[0], x1[1]); w.w = cvt_pk_bf16(x1[2], x1[3]);
;                     *(u32x4*)(XB + off + bj * HALF) = w; }
;                 ss += __shfl_xor(ss, 16); ss += __shfl_xor(ss, 32);
;                 if (fq == 0) SSQ[r * 64 + u.pn * 4 + wc] = ss; }
.LBB0_245:
	s_or_b64 exec, exec, s[60:61]
	v_add_u32_e32 v66, 0x80, v138
	s_waitcnt lgkmcnt(0)
	v_ashrrev_i32_e32 v67, 31, v66
	v_lshlrev_b64 v[68:69], 12, v[66:67]
	v_lshl_add_u64 v[84:85], v[68:69], 0, v[136:137]
	v_lshlrev_b64 v[86:87], 2, v[84:85]
	v_lshl_add_u64 v[88:89], s[8:9], 0, v[86:87]
	global_load_dwordx4 v[68:71], v[88:89], off nt
	global_load_dwordx4 v[72:75], v[88:89], off offset:16 nt
	global_load_dwordx4 v[76:79], v[134:135], off
	global_load_dwordx4 v[80:83], v[134:135], off offset:16
	v_lshl_add_u64 v[84:85], v[84:85], 1, s[20:21]
	v_lshl_add_u64 v[86:87], s[26:27], 0, v[86:87]
	s_waitcnt vmcnt(3)
	v_pk_fma_f32 v[64:65], v[64:65], 0.5, v[70:71] op_sel_hi:[1,0,1]
	v_pk_fma_f32 v[62:63], v[62:63], 0.5, v[68:69] op_sel_hi:[1,0,1]
	s_waitcnt vmcnt(2)
	v_pk_fma_f32 v[60:61], v[60:61], 0.5, v[74:75] op_sel_hi:[1,0,1]
	v_pk_fma_f32 v[58:59], v[58:59], 0.5, v[72:73] op_sel_hi:[1,0,1]
	s_waitcnt vmcnt(1)
	v_pk_mul_f32 v[70:71], v[78:79], v[64:65]
	v_pk_mul_f32 v[68:69], v[76:77], v[62:63]
	global_store_dwordx4 v[86:87], v[62:65], off nt
	global_store_dwordx4 v[86:87], v[58:61], off offset:16 nt
	s_waitcnt vmcnt(2)
	v_pk_mul_f32 v[72:73], v[82:83], v[60:61]
	v_pk_mul_f32 v[74:75], v[80:81], v[58:59]
	v_cvt_pk_bf16_f32 v68, v68, v69
	v_cvt_pk_bf16_f32 v69, v70, v71
	v_mul_f32_e32 v63, v63, v63
	v_cvt_pk_bf16_f32 v70, v74, v75
	v_cvt_pk_bf16_f32 v71, v72, v73
	global_store_dwordx4 v[84:85], v[68:71], off
	global_load_dwordx4 v[68:71], v[88:89], off offset:512
	s_nop 0
	global_load_dwordx4 v[72:75], v[88:89], off offset:528
	global_load_dwordx4 v[76:79], v[134:135], off offset:512
	global_load_dwordx4 v[80:83], v[134:135], off offset:528
	v_mul_f32_e32 v65, v65, v65
	v_mul_f32_e32 v59, v59, v59
	v_fmac_f32_e32 v63, v62, v62
	v_fmac_f32_e32 v65, v64, v64
	v_mul_f32_e32 v61, v61, v61
	v_fmac_f32_e32 v59, v58, v58
	v_add_f32_e32 v58, v63, v65
	v_fmac_f32_e32 v61, v60, v60
	v_add_f32_e32 v58, v59, v58
	v_add_f32_e32 v58, v61, v58
	s_waitcnt vmcnt(3)
	v_pk_fma_f32 v[56:57], v[56:57], 0.5, v[70:71] op_sel_hi:[1,0,1]
	v_pk_fma_f32 v[54:55], v[54:55], 0.5, v[68:69] op_sel_hi:[1,0,1]
	s_waitcnt vmcnt(2)
	v_pk_fma_f32 v[50:51], v[50:51], 0.5, v[72:73] op_sel_hi:[1,0,1]
	v_mul_f32_e32 v59, v55, v55
	v_mul_f32_e32 v60, v57, v57
	v_pk_fma_f32 v[52:53], v[52:53], 0.5, v[74:75] op_sel_hi:[1,0,1]
	v_mul_f32_e32 v61, v51, v51
	v_fmac_f32_e32 v59, v54, v54
	v_fmac_f32_e32 v60, v56, v56
	v_mul_f32_e32 v62, v53, v53
	v_fmac_f32_e32 v61, v50, v50
	v_add_f32_e32 v59, v59, v60
	v_fmac_f32_e32 v62, v52, v52
	v_add_f32_e32 v59, v61, v59
	v_add_f32_e32 v59, v62, v59
	v_add_f32_e32 v62, v58, v59
	ds_bpermute_b32 v63, v122, v62
	global_store_dwordx4 v[86:87], v[54:57], off offset:512 nt
	global_store_dwordx4 v[86:87], v[50:53], off offset:528 nt
	s_waitcnt vmcnt(2)
	v_pk_mul_f32 v[60:61], v[80:81], v[50:51]
	v_pk_mul_f32 v[54:55], v[76:77], v[54:55]
	v_pk_mul_f32 v[56:57], v[78:79], v[56:57]
	s_waitcnt lgkmcnt(0)
	v_add_f32_e32 v50, v62, v63
	ds_bpermute_b32 v51, v116, v50
	v_pk_mul_f32 v[58:59], v[82:83], v[52:53]
	v_cvt_pk_bf16_f32 v52, v54, v55
	v_cvt_pk_bf16_f32 v53, v56, v57
	v_cvt_pk_bf16_f32 v54, v60, v61
	s_nop 0
	v_cvt_pk_bf16_f32 v55, v58, v59
	global_store_dwordx4 v[84:85], v[52:55], off offset:256
	s_and_saveexec_b64 s[60:61], s[0:1]
	s_cbranch_execz .LBB0_247
	v_lshlrev_b64 v[52:53], 8, v[66:67]
	v_lshl_add_u64 v[52:53], s[38:39], 0, v[52:53]
	v_lshl_add_u64 v[52:53], s[50:51], 2, v[52:53]
	s_lshl_b32 s12, s87, 2
	v_lshl_add_u64 v[52:53], v[52:53], 0, s[12:13]
	s_waitcnt lgkmcnt(0)
	v_add_f32_e32 v50, v50, v51
	global_store_dword v[52:53], v50, off
.LBB0_247:
	s_or_b64 exec, exec, s[60:61]
	v_add_u32_e32 v50, 0x90, v138
	s_waitcnt lgkmcnt(0)
	v_ashrrev_i32_e32 v51, 31, v50
	v_lshlrev_b64 v[52:53], 12, v[50:51]
	v_lshl_add_u64 v[68:69], v[52:53], 0, v[136:137]
	v_lshlrev_b64 v[70:71], 2, v[68:69]
	v_lshl_add_u64 v[72:73], s[8:9], 0, v[70:71]
	global_load_dwordx4 v[52:55], v[72:73], off nt
	global_load_dwordx4 v[56:59], v[72:73], off offset:16 nt
	global_load_dwordx4 v[60:63], v[134:135], off
	global_load_dwordx4 v[64:67], v[134:135], off offset:16
	v_lshl_add_u64 v[68:69], v[68:69], 1, s[20:21]
	v_lshl_add_u64 v[70:71], s[26:27], 0, v[70:71]
	s_waitcnt vmcnt(3)
	v_pk_fma_f32 v[48:49], v[48:49], 0.5, v[54:55] op_sel_hi:[1,0,1]
	v_pk_fma_f32 v[46:47], v[46:47], 0.5, v[52:53] op_sel_hi:[1,0,1]
	s_waitcnt vmcnt(2)
	v_pk_fma_f32 v[44:45], v[44:45], 0.5, v[58:59] op_sel_hi:[1,0,1]
	v_pk_fma_f32 v[42:43], v[42:43], 0.5, v[56:57] op_sel_hi:[1,0,1]
	s_waitcnt vmcnt(1)
	v_pk_mul_f32 v[54:55], v[62:63], v[48:49]
	v_pk_mul_f32 v[52:53], v[60:61], v[46:47]
	global_store_dwordx4 v[70:71], v[46:49], off nt
	global_store_dwordx4 v[70:71], v[42:45], off offset:16 nt
	s_waitcnt vmcnt(2)
	v_pk_mul_f32 v[56:57], v[66:67], v[44:45]
	v_pk_mul_f32 v[58:59], v[64:65], v[42:43]
	v_cvt_pk_bf16_f32 v52, v52, v53
	v_cvt_pk_bf16_f32 v53, v54, v55
	v_mul_f32_e32 v47, v47, v47
	v_cvt_pk_bf16_f32 v54, v58, v59
	v_cvt_pk_bf16_f32 v55, v56, v57
	global_store_dwordx4 v[68:69], v[52:55], off
	global_load_dwordx4 v[52:55], v[72:73], off offset:512
	s_nop 0
	global_load_dwordx4 v[56:59], v[72:73], off offset:528
	global_load_dwordx4 v[60:63], v[134:135], off offset:512
	global_load_dwordx4 v[64:67], v[134:135], off offset:528
	v_mul_f32_e32 v49, v49, v49
	v_mul_f32_e32 v43, v43, v43
	v_fmac_f32_e32 v47, v46, v46
	v_fmac_f32_e32 v49, v48, v48
	v_mul_f32_e32 v45, v45, v45
	v_fmac_f32_e32 v43, v42, v42
	v_add_f32_e32 v42, v47, v49
	v_fmac_f32_e32 v45, v44, v44
	v_add_f32_e32 v42, v43, v42
	v_add_f32_e32 v42, v45, v42
	s_waitcnt vmcnt(3)
	v_pk_fma_f32 v[40:41], v[40:41], 0.5, v[54:55] op_sel_hi:[1,0,1]
	v_pk_fma_f32 v[38:39], v[38:39], 0.5, v[52:53] op_sel_hi:[1,0,1]
	s_waitcnt vmcnt(2)
	v_pk_fma_f32 v[34:35], v[34:35], 0.5, v[56:57] op_sel_hi:[1,0,1]
	v_mul_f32_e32 v43, v39, v39
	v_mul_f32_e32 v44, v41, v41
	v_pk_fma_f32 v[36:37], v[36:37], 0.5, v[58:59] op_sel_hi:[1,0,1]
	v_mul_f32_e32 v45, v35, v35
	v_fmac_f32_e32 v43, v38, v38
	v_fmac_f32_e32 v44, v40, v40
	v_mul_f32_e32 v46, v37, v37
	v_fmac_f32_e32 v45, v34, v34
	v_add_f32_e32 v43, v43, v44
	v_fmac_f32_e32 v46, v36, v36
	v_add_f32_e32 v43, v45, v43
	v_add_f32_e32 v43, v46, v43
	v_add_f32_e32 v46, v42, v43
	ds_bpermute_b32 v47, v122, v46
	global_store_dwordx4 v[70:71], v[38:41], off offset:512 nt
	global_store_dwordx4 v[70:71], v[34:37], off offset:528 nt
	s_waitcnt vmcnt(2)
	v_pk_mul_f32 v[44:45], v[64:65], v[34:35]
	v_pk_mul_f32 v[38:39], v[60:61], v[38:39]
	v_pk_mul_f32 v[40:41], v[62:63], v[40:41]
	s_waitcnt lgkmcnt(0)
	v_add_f32_e32 v34, v46, v47
	ds_bpermute_b32 v35, v116, v34
	v_pk_mul_f32 v[42:43], v[66:67], v[36:37]
	v_cvt_pk_bf16_f32 v36, v38, v39
	v_cvt_pk_bf16_f32 v37, v40, v41
	v_cvt_pk_bf16_f32 v38, v44, v45
	s_nop 0
	v_cvt_pk_bf16_f32 v39, v42, v43
	global_store_dwordx4 v[68:69], v[36:39], off offset:256
	s_and_saveexec_b64 s[60:61], s[0:1]
	s_cbranch_execz .LBB0_249
; __device__ __forceinline__ unsigned cvt_pk_bf16(float lo, float hi) { unsigned r; asm volatile("v_cvt_pk_bf16_f32 %0, %1, %2" : "=v"(r) : "v"(lo), "v"(hi)); return r; }
;     __device__ __forceinline__ void operator()(const f32x4 (&acc)[2][2][4][2], const Unit& u, int wr, int wc, int fr, int fq) const {
;     ...
;             for (int m = 0; m < 4; ++m) { const size_t r = (size_t)(row0 + ai * HALF + m * 16); const size_t off = r * ldc + col0; float ss = 0.f;
; #pragma unroll
;                 for (int bj = 0; bj < 2; ++bj) { const f32x4 b0 = *(const f32x4*)(base + off + bj * HALF), b1 = *(const f32x4*)(base + off + bj * HALF + 4);
;                     const f32x4 g0 = *(const f32x4*)(gain + col0 + bj * HALF), g1 = *(const f32x4*)(gain + col0 + bj * HALF + 4);
;                     const f32x4 v0 = b0 + acc[ai][bj][m][0] * alpha, v1 = b1 + acc[ai][bj][m][1] * alpha;
;                     *(f32x4*)(out + off + bj * HALF) = v0; *(f32x4*)(out + off + bj * HALF + 4) = v1;
;                     ss += (v0[0] * v0[0] + v0[1] * v0[1]) + (v0[2] * v0[2] + v0[3] * v0[3]) + (v1[0] * v1[0] + v1[1] * v1[1]) + (v1[2] * v1[2] + v1[3] * v1[3]);
;                     const f32x4 x0 = v0 * g0, x1 = v1 * g1;
;                     u32x4 w; w.x = cvt_pk_bf16(x0[0], x0[1]); w.y = cvt_pk_bf16(x0[2], x0[3]); w.z = cvt_pk_bf16(x1[0], x1[1]); w.w = cvt_pk_bf16(x1[2], x1[3]);
;                     *(u32x4*)(XB + off + bj * HALF) = w; }
;                 ss += __shfl_xor(ss, 16); ss += __shfl_xor(ss, 32);
;                 if (fq == 0) SSQ[r * 64 + u.pn * 4 + wc] = ss; }
	v_lshlrev_b64 v[36:37], 8, v[50:51]
	v_lshl_add_u64 v[36:37], s[38:39], 0, v[36:37]
	v_lshl_add_u64 v[36:37], s[50:51], 2, v[36:37]
	s_lshl_b32 s12, s87, 2
	v_lshl_add_u64 v[36:37], v[36:37], 0, s[12:13]
	s_waitcnt lgkmcnt(0)
	v_add_f32_e32 v34, v34, v35
	global_store_dword v[36:37], v34, off
.LBB0_249:
	s_or_b64 exec, exec, s[60:61]
	v_add_u32_e32 v34, 0xa0, v138
	s_waitcnt lgkmcnt(0)
	v_ashrrev_i32_e32 v35, 31, v34
	v_lshlrev_b64 v[36:37], 12, v[34:35]
	v_lshl_add_u64 v[52:53], v[36:37], 0, v[136:137]
	v_lshlrev_b64 v[54:55], 2, v[52:53]
	v_lshl_add_u64 v[56:57], s[8:9], 0, v[54:55]
	global_load_dwordx4 v[36:39], v[56:57], off nt
	global_load_dwordx4 v[40:43], v[56:57], off offset:16 nt
	global_load_dwordx4 v[44:47], v[134:135], off
	global_load_dwordx4 v[48:51], v[134:135], off offset:16
	v_lshl_add_u64 v[52:53], v[52:53], 1, s[20:21]
	v_lshl_add_u64 v[54:55], s[26:27], 0, v[54:55]
	s_waitcnt vmcnt(3)
	v_pk_fma_f32 v[32:33], v[32:33], 0.5, v[38:39] op_sel_hi:[1,0,1]
	v_pk_fma_f32 v[30:31], v[30:31], 0.5, v[36:37] op_sel_hi:[1,0,1]
	s_waitcnt vmcnt(2)
	v_pk_fma_f32 v[28:29], v[28:29], 0.5, v[42:43] op_sel_hi:[1,0,1]
	v_pk_fma_f32 v[26:27], v[26:27], 0.5, v[40:41] op_sel_hi:[1,0,1]
	s_waitcnt vmcnt(1)
	v_pk_mul_f32 v[38:39], v[46:47], v[32:33]
	v_pk_mul_f32 v[36:37], v[44:45], v[30:31]
	global_store_dwordx4 v[54:55], v[30:33], off nt
	global_store_dwordx4 v[54:55], v[26:29], off offset:16 nt
	s_waitcnt vmcnt(2)
	v_pk_mul_f32 v[40:41], v[50:51], v[28:29]
	v_pk_mul_f32 v[42:43], v[48:49], v[26:27]
	v_cvt_pk_bf16_f32 v36, v36, v37
	v_cvt_pk_bf16_f32 v37, v38, v39
	v_mul_f32_e32 v31, v31, v31
	v_cvt_pk_bf16_f32 v38, v42, v43
	v_cvt_pk_bf16_f32 v39, v40, v41
	global_store_dwordx4 v[52:53], v[36:39], off
	global_load_dwordx4 v[36:39], v[56:57], off offset:512
	s_nop 0
	global_load_dwordx4 v[40:43], v[56:57], off offset:528
	global_load_dwordx4 v[44:47], v[134:135], off offset:512
	global_load_dwordx4 v[48:51], v[134:135], off offset:528
	v_mul_f32_e32 v33, v33, v33
	v_mul_f32_e32 v27, v27, v27
	v_fmac_f32_e32 v31, v30, v30
	v_fmac_f32_e32 v33, v32, v32
	v_mul_f32_e32 v29, v29, v29
	v_fmac_f32_e32 v27, v26, v26
	v_add_f32_e32 v26, v31, v33
	v_fmac_f32_e32 v29, v28, v28
	v_add_f32_e32 v26, v27, v26
	v_add_f32_e32 v26, v29, v26
	s_waitcnt vmcnt(3)
	v_pk_fma_f32 v[24:25], v[24:25], 0.5, v[38:39] op_sel_hi:[1,0,1]
	v_pk_fma_f32 v[22:23], v[22:23], 0.5, v[36:37] op_sel_hi:[1,0,1]
	s_waitcnt vmcnt(2)
	v_pk_fma_f32 v[18:19], v[18:19], 0.5, v[40:41] op_sel_hi:[1,0,1]
	v_mul_f32_e32 v27, v23, v23
	v_mul_f32_e32 v28, v25, v25
	v_pk_fma_f32 v[20:21], v[20:21], 0.5, v[42:43] op_sel_hi:[1,0,1]
	v_mul_f32_e32 v29, v19, v19
	v_fmac_f32_e32 v27, v22, v22
	v_fmac_f32_e32 v28, v24, v24
	v_mul_f32_e32 v30, v21, v21
	v_fmac_f32_e32 v29, v18, v18
	v_add_f32_e32 v27, v27, v28
	v_fmac_f32_e32 v30, v20, v20
	v_add_f32_e32 v27, v29, v27
	v_add_f32_e32 v27, v30, v27
	v_add_f32_e32 v30, v26, v27
	ds_bpermute_b32 v31, v122, v30
	global_store_dwordx4 v[54:55], v[22:25], off offset:512 nt
	global_store_dwordx4 v[54:55], v[18:21], off offset:528 nt
	s_waitcnt vmcnt(2)
	v_pk_mul_f32 v[28:29], v[48:49], v[18:19]
	v_pk_mul_f32 v[22:23], v[44:45], v[22:23]
	v_pk_mul_f32 v[24:25], v[46:47], v[24:25]
	s_waitcnt lgkmcnt(0)
	v_add_f32_e32 v18, v30, v31
	ds_bpermute_b32 v19, v116, v18
	v_pk_mul_f32 v[26:27], v[50:51], v[20:21]
	v_cvt_pk_bf16_f32 v20, v22, v23
	v_cvt_pk_bf16_f32 v21, v24, v25
	v_cvt_pk_bf16_f32 v22, v28, v29
	s_nop 0
	v_cvt_pk_bf16_f32 v23, v26, v27
	global_store_dwordx4 v[52:53], v[20:23], off offset:256
	s_and_saveexec_b64 s[60:61], s[0:1]
	s_cbranch_execz .LBB0_251
	v_lshlrev_b64 v[20:21], 8, v[34:35]
	v_lshl_add_u64 v[20:21], s[38:39], 0, v[20:21]
	v_lshl_add_u64 v[20:21], s[50:51], 2, v[20:21]
	s_lshl_b32 s12, s87, 2
	v_lshl_add_u64 v[20:21], v[20:21], 0, s[12:13]
	s_waitcnt lgkmcnt(0)
	v_add_f32_e32 v18, v18, v19
	global_store_dword v[20:21], v18, off
; __device__ __forceinline__ unsigned cvt_pk_bf16(float lo, float hi) { unsigned r; asm volatile("v_cvt_pk_bf16_f32 %0, %1, %2" : "=v"(r) : "v"(lo), "v"(hi)); return r; }
;     __device__ __forceinline__ void operator()(const f32x4 (&acc)[2][2][4][2], const Unit& u, int wr, int wc, int fr, int fq) const {
;     ...
;             for (int m = 0; m < 4; ++m) { const size_t r = (size_t)(row0 + ai * HALF + m * 16); const size_t off = r * ldc + col0; float ss = 0.f;
; #pragma unroll
;                 for (int bj = 0; bj < 2; ++bj) { const f32x4 b0 = *(const f32x4*)(base + off + bj * HALF), b1 = *(const f32x4*)(base + off + bj * HALF + 4);
;                     const f32x4 g0 = *(const f32x4*)(gain + col0 + bj * HALF), g1 = *(const f32x4*)(gain + col0 + bj * HALF + 4);
;                     const f32x4 v0 = b0 + acc[ai][bj][m][0] * alpha, v1 = b1 + acc[ai][bj][m][1] * alpha;
;                     *(f32x4*)(out + off + bj * HALF) = v0; *(f32x4*)(out + off + bj * HALF + 4) = v1;
;                     ss += (v0[0] * v0[0] + v0[1] * v0[1]) + (v0[2] * v0[2] + v0[3] * v0[3]) + (v1[0] * v1[0] + v1[1] * v1[1]) + (v1[2] * v1[2] + v1[3] * v1[3]);
;                     const f32x4 x0 = v0 * g0, x1 = v1 * g1;
;                     u32x4 w; w.x = cvt_pk_bf16(x0[0], x0[1]); w.y = cvt_pk_bf16(x0[2], x0[3]); w.z = cvt_pk_bf16(x1[0], x1[1]); w.w = cvt_pk_bf16(x1[2], x1[3]);
;                     *(u32x4*)(XB + off + bj * HALF) = w; }
;                 ss += __shfl_xor(ss, 16); ss += __shfl_xor(ss, 32);
;                 if (fq == 0) SSQ[r * 64 + u.pn * 4 + wc] = ss; }
.LBB0_251:
	s_or_b64 exec, exec, s[60:61]
	v_add_u32_e32 v18, 0xb0, v138
	s_waitcnt lgkmcnt(0)
	v_ashrrev_i32_e32 v19, 31, v18
	v_lshlrev_b64 v[20:21], 12, v[18:19]
	v_lshl_add_u64 v[36:37], v[20:21], 0, v[136:137]
	v_lshlrev_b64 v[38:39], 2, v[36:37]
	v_lshl_add_u64 v[40:41], s[8:9], 0, v[38:39]
	global_load_dwordx4 v[20:23], v[40:41], off nt
	global_load_dwordx4 v[24:27], v[40:41], off offset:16 nt
	global_load_dwordx4 v[28:31], v[134:135], off
	global_load_dwordx4 v[32:35], v[134:135], off offset:16
	v_lshl_add_u64 v[36:37], v[36:37], 1, s[20:21]
	v_lshl_add_u64 v[38:39], s[26:27], 0, v[38:39]
	s_waitcnt vmcnt(3)
	v_pk_fma_f32 v[16:17], v[16:17], 0.5, v[22:23] op_sel_hi:[1,0,1]
	v_pk_fma_f32 v[14:15], v[14:15], 0.5, v[20:21] op_sel_hi:[1,0,1]
	s_waitcnt vmcnt(2)
	v_pk_fma_f32 v[12:13], v[12:13], 0.5, v[26:27] op_sel_hi:[1,0,1]
	v_pk_fma_f32 v[10:11], v[10:11], 0.5, v[24:25] op_sel_hi:[1,0,1]
	s_waitcnt vmcnt(1)
	v_pk_mul_f32 v[22:23], v[30:31], v[16:17]
	v_pk_mul_f32 v[20:21], v[28:29], v[14:15]
	global_store_dwordx4 v[38:39], v[14:17], off nt
	global_store_dwordx4 v[38:39], v[10:13], off offset:16 nt
	s_waitcnt vmcnt(2)
	v_pk_mul_f32 v[24:25], v[34:35], v[12:13]
	v_pk_mul_f32 v[26:27], v[32:33], v[10:11]
	v_cvt_pk_bf16_f32 v20, v20, v21
	v_cvt_pk_bf16_f32 v21, v22, v23
	v_mul_f32_e32 v15, v15, v15
	v_cvt_pk_bf16_f32 v22, v26, v27
	v_cvt_pk_bf16_f32 v23, v24, v25
	global_store_dwordx4 v[36:37], v[20:23], off
	global_load_dwordx4 v[20:23], v[40:41], off offset:512
	s_nop 0
	global_load_dwordx4 v[24:27], v[40:41], off offset:528
	global_load_dwordx4 v[28:31], v[134:135], off offset:512
	global_load_dwordx4 v[32:35], v[134:135], off offset:528
	v_mul_f32_e32 v17, v17, v17
	v_mul_f32_e32 v11, v11, v11
	v_fmac_f32_e32 v15, v14, v14
	v_fmac_f32_e32 v17, v16, v16
	v_mul_f32_e32 v13, v13, v13
	v_fmac_f32_e32 v11, v10, v10
	v_add_f32_e32 v10, v15, v17
	v_fmac_f32_e32 v13, v12, v12
	v_add_f32_e32 v10, v11, v10
	v_add_f32_e32 v10, v13, v10
	s_waitcnt vmcnt(3)
	v_pk_fma_f32 v[8:9], v[8:9], 0.5, v[22:23] op_sel_hi:[1,0,1]
	v_pk_fma_f32 v[6:7], v[6:7], 0.5, v[20:21] op_sel_hi:[1,0,1]
	s_waitcnt vmcnt(2)
	v_pk_fma_f32 v[2:3], v[2:3], 0.5, v[24:25] op_sel_hi:[1,0,1]
	v_mul_f32_e32 v11, v7, v7
	v_mul_f32_e32 v12, v9, v9
	v_pk_fma_f32 v[4:5], v[4:5], 0.5, v[26:27] op_sel_hi:[1,0,1]
	v_mul_f32_e32 v13, v3, v3
	v_fmac_f32_e32 v11, v6, v6
	v_fmac_f32_e32 v12, v8, v8
	v_mul_f32_e32 v14, v5, v5
	v_fmac_f32_e32 v13, v2, v2
	v_add_f32_e32 v11, v11, v12
	v_fmac_f32_e32 v14, v4, v4
	v_add_f32_e32 v11, v13, v11
	v_add_f32_e32 v11, v14, v11
	v_add_f32_e32 v14, v10, v11
	ds_bpermute_b32 v15, v122, v14
	global_store_dwordx4 v[38:39], v[6:9], off offset:512 nt
	global_store_dwordx4 v[38:39], v[2:5], off offset:528 nt
	s_waitcnt vmcnt(2)
	v_pk_mul_f32 v[12:13], v[32:33], v[2:3]
	v_pk_mul_f32 v[6:7], v[28:29], v[6:7]
	v_pk_mul_f32 v[8:9], v[30:31], v[8:9]
	s_waitcnt lgkmcnt(0)
	v_add_f32_e32 v2, v14, v15
	ds_bpermute_b32 v3, v116, v2
	v_pk_mul_f32 v[10:11], v[34:35], v[4:5]
	v_cvt_pk_bf16_f32 v4, v6, v7
	v_cvt_pk_bf16_f32 v5, v8, v9
	v_cvt_pk_bf16_f32 v6, v12, v13
	s_nop 0
	v_cvt_pk_bf16_f32 v7, v10, v11
	global_store_dwordx4 v[36:37], v[4:7], off offset:256
	s_and_saveexec_b64 s[60:61], s[0:1]
	s_cbranch_execz .LBB0_253
	v_lshlrev_b64 v[4:5], 8, v[18:19]
	v_lshl_add_u64 v[4:5], s[38:39], 0, v[4:5]
	v_lshl_add_u64 v[4:5], s[50:51], 2, v[4:5]
	s_lshl_b32 s12, s87, 2
	v_lshl_add_u64 v[4:5], v[4:5], 0, s[12:13]
	s_waitcnt lgkmcnt(0)
	v_add_f32_e32 v2, v2, v3
	global_store_dword v[4:5], v2, off

;     __host__ __device__ bool next(int i, Unit& u) const {
;         const long L = (long)i * G + c; if (L >= nwg) return false;
;         int wgid = (int)L; { const int q = nwg / NXCD, r = nwg % NXCD, xcd = wgid % NXCD, off = wgid / NXCD; wgid = (xcd < r ? xcd * (q + 1) : r * (q + 1) + (xcd - r) * q) + off; }
;         const int nig = WGM * nN, gid = wgid / nig, fm = gid * WGM, gsz = (nM - fm) < WGM ? (nM - fm) : WGM;
;         u.pm = fm + ((wgid % nig) % gsz); u.pn = (wgid % nig) / gsz; return true;
;     __device__ __forceinline__ void a_ready(const Unit& u) const {
;         if ((slot ? pm1 : pm0) == u.pm) return;
;         slot ^= 1; if (slot) pm1 = u.pm; else pm0 = u.pm;
;         const int t = threadIdx.x, row = t >> 1, part = t & 1;
;         const f32x4* p = (const f32x4*)(ssq + (size_t)(u.pm * BM + row) * 64 + part * 32);
;         float s = 0.f;
; #pragma unroll
;         for (int j = 0; j < 8; ++j) { const f32x4 v = p[j]; s += (v[0] + v[1]) + (v[2] + v[3]); }
;         s += __shfl_xor(s, 1);
;         if (part == 0) tab[slot * 256 + row] = 1.0f / sqrtf(s * inv_n + eps);
;         asm volatile("s_waitcnt lgkmcnt(0)" ::: "memory"); __builtin_amdgcn_s_barrier(); asm volatile("" ::: "memory");
.LBB0_307:
	s_cmp_lt_i32 s30, 4
	s_cselect_b64 s[4:5], -1, 0
	s_add_u32 s10, s28, 0x56f80000
	s_addc_u32 s11, s29, 0
	s_and_b64 s[12:13], s[4:5], s[0:1]
	s_andn2_b64 vcc, exec, s[12:13]
	s_cbranch_vccnz .LBB0_335
	v_readfirstlane_b32 s3, v0
	s_cmpk_gt_i32 s2, 0x9ff
	v_and_b32_e32 v1, 15, v0
	s_cbranch_scc1 .LBB0_330
	s_ashr_i32 s35, s2, 31
	s_lshr_b32 s0, s35, 29
	s_add_i32 s0, s2, s0
	s_ashr_i32 s1, s0, 3
	s_and_b32 s0, s0, -8
	s_sub_i32 s0, s2, s0
	s_cmp_lt_i32 s0, 0
	s_movk_i32 s4, 0x141
	s_cselect_b32 s4, s4, 0x140
	s_mul_i32 s0, s0, s4
	s_add_i32 s0, s0, s1
	s_mul_hi_i32 s1, s0, 0x66666667
	s_lshr_b32 s4, s1, 31
	s_ashr_i32 s1, s1, 8
	s_add_i32 s1, s1, s4
	s_lshl_b32 s4, s1, 3
	s_mulk_i32 s1, 0x280
	s_sub_i32 s0, s0, s1
	s_sext_i32_i16 s1, s0
	s_bfe_u32 s1, s1, 0x3001c
	s_add_i32 s1, s0, s1
	s_and_b32 s5, s1, 0xfff8
	s_sub_i32 s0, s0, s5
	s_sext_i32_i16 s0, s0
	s_add_i32 s14, s4, s0
	v_lshrrev_b32_e32 v140, 1, v0
	s_mov_b32 s64, 0
	s_cmp_eq_u32 s14, -1
	s_sext_i32_i16 s6, s1
	s_cbranch_scc1 .LBB0_313
	v_lshl_or_b32 v2, s14, 8, v140
	s_waitcnt lgkmcnt(0)
	v_ashrrev_i32_e32 v3, 31, v2
	v_and_b32_e32 v34, 1, v0
	v_lshlrev_b64 v[2:3], 8, v[2:3]
	v_lshl_add_u64 v[2:3], s[38:39], 0, v[2:3]
	v_lshlrev_b32_e32 v4, 7, v34
	v_mov_b32_e32 v5, 0
	v_lshl_add_u64 v[30:31], v[2:3], 0, v[4:5]
	global_load_dwordx4 v[2:5], v[30:31], off nt
	global_load_dwordx4 v[6:9], v[30:31], off offset:16 nt
	global_load_dwordx4 v[10:13], v[30:31], off offset:32 nt
	global_load_dwordx4 v[14:17], v[30:31], off offset:48 nt
	global_load_dwordx4 v[18:21], v[30:31], off offset:64 nt
	global_load_dwordx4 v[22:25], v[30:31], off offset:80 nt
	global_load_dwordx4 v[26:29], v[30:31], off offset:96
	s_nop 0
	global_load_dwordx4 v[30:33], v[30:31], off offset:112
	v_mbcnt_lo_u32_b32 v35, -1, 0
	v_mbcnt_hi_u32_b32 v35, -1, v35
	v_and_b32_e32 v37, 64, v35
	v_xor_b32_e32 v36, 1, v35
	v_add_u32_e32 v37, 64, v37
	v_cmp_lt_i32_e32 vcc, v36, v37
	s_waitcnt vmcnt(7)
	v_add_f32_e32 v2, v2, v3
	v_add_f32_e32 v3, v4, v5
	s_waitcnt vmcnt(6)
	v_add_f32_e32 v4, v6, v7
	v_add_f32_e32 v5, v8, v9
	v_add_f32_e32 v2, v2, v3
	s_waitcnt vmcnt(5)
	v_add_f32_e32 v6, v10, v11
	v_add_f32_e32 v7, v12, v13
	v_add_f32_e32 v3, v4, v5
	v_add_f32_e32 v2, 0, v2
	s_waitcnt vmcnt(4)
	v_add_f32_e32 v8, v14, v15
	v_add_f32_e32 v9, v16, v17
	v_add_f32_e32 v4, v6, v7
	v_add_f32_e32 v2, v2, v3
	s_waitcnt vmcnt(3)
	v_add_f32_e32 v10, v18, v19
	v_add_f32_e32 v11, v20, v21
	v_add_f32_e32 v5, v8, v9
	v_add_f32_e32 v2, v2, v4
	s_waitcnt vmcnt(2)
	v_add_f32_e32 v12, v22, v23
	v_add_f32_e32 v13, v24, v25
	v_add_f32_e32 v6, v10, v11
	v_add_f32_e32 v2, v2, v5
	s_waitcnt vmcnt(1)
	v_add_f32_e32 v14, v26, v27
	v_add_f32_e32 v15, v28, v29
	v_add_f32_e32 v7, v12, v13
	v_add_f32_e32 v2, v2, v6
	s_waitcnt vmcnt(0)
	v_add_f32_e32 v16, v30, v31
	v_add_f32_e32 v17, v32, v33
	v_add_f32_e32 v8, v14, v15
	v_add_f32_e32 v2, v2, v7
	v_cndmask_b32_e32 v35, v35, v36, vcc
	v_add_f32_e32 v9, v16, v17
	v_add_f32_e32 v2, v2, v8
	v_add_f32_e32 v2, v2, v9
	v_lshlrev_b32_e32 v3, 2, v35
	ds_bpermute_b32 v3, v3, v2
	v_cmp_eq_u32_e32 vcc, 0, v34
	s_and_saveexec_b64 s[4:5], vcc
	s_cbranch_execz .LBB0_312
	s_waitcnt lgkmcnt(0)
	v_add_f32_e32 v2, v2, v3
	v_mov_b32_e32 v3, 0x358637bd
	v_fmac_f32_e32 v3, 0x39800000, v2
	s_mov_b32 s0, 0xf800000
	v_mul_f32_e32 v2, 0x4f800000, v3
	v_cmp_gt_f32_e32 vcc, s0, v3
	s_nop 1
	v_cndmask_b32_e32 v2, v3, v2, vcc
	v_sqrt_f32_e32 v3, v2
	s_nop 0
	v_add_u32_e32 v4, -1, v3
	v_fma_f32 v5, -v4, v3, v2
	v_cmp_ge_f32_e64 s[0:1], 0, v5
	v_add_u32_e32 v5, 1, v3
	s_nop 0
	v_cndmask_b32_e64 v4, v3, v4, s[0:1]
	v_fma_f32 v3, -v5, v3, v2
	v_cmp_lt_f32_e64 s[0:1], 0, v3
	s_nop 1
	v_cndmask_b32_e64 v3, v4, v5, s[0:1]
	v_mul_f32_e32 v4, 0x37800000, v3
	v_cndmask_b32_e32 v3, v3, v4, vcc
	v_mov_b32_e32 v4, 0x260
	v_cmp_class_f32_e32 vcc, v2, v4
	s_nop 1
	v_cndmask_b32_e32 v2, v3, v2, vcc
	v_div_scale_f32 v3, s[0:1], v2, v2, 1.0
	v_rcp_f32_e32 v4, v3
	s_nop 0
	v_fma_f32 v5, -v3, v4, 1.0
	v_fmac_f32_e32 v4, v5, v4
	v_div_scale_f32 v5, vcc, 1.0, v2, 1.0
	v_mul_f32_e32 v6, v5, v4
	v_fma_f32 v7, -v3, v6, v5
	v_fmac_f32_e32 v6, v7, v4
	v_fma_f32 v3, -v3, v6, v5
	v_div_fmas_f32 v3, v3, v4, v6
	v_div_fixup_f32 v2, v3, v2, 1.0
	v_lshl_add_u32 v3, v140, 2, 0
	v_add_u32_e32 v3, 0x20400, v3
	ds_write_b32 v3, v2

;     __device__ __forceinline__ void a_ready(const Unit& u) const {
;         if ((slot ? pm1 : pm0) == u.pm) return;
;         slot ^= 1; if (slot) pm1 = u.pm; else pm0 = u.pm;
;         const int t = threadIdx.x, row = t >> 1, part = t & 1;
;         const f32x4* p = (const f32x4*)(ssq + (size_t)(u.pm * BM + row) * 64 + part * 32);
;         float s = 0.f;
; #pragma unroll
;         for (int j = 0; j < 8; ++j) { const f32x4 v = p[j]; s += (v[0] + v[1]) + (v[2] + v[3]); }
;         s += __shfl_xor(s, 1);
;         if (part == 0) tab[slot * 256 + row] = 1.0f / sqrtf(s * inv_n + eps);
;         asm volatile("s_waitcnt lgkmcnt(0)" ::: "memory"); __builtin_amdgcn_s_barrier(); asm volatile("" ::: "memory");
.LBB0_320:
	s_cmp_eq_u32 s58, 60
	s_cselect_b64 s[62:63], -1, 0
	s_and_b64 s[8:9], s[4:5], s[62:63]
	s_andn2_b64 vcc, exec, s[8:9]
	s_cbranch_vccnz .LBB0_325
	s_cmp_eq_u32 s64, 0
	s_cselect_b32 s8, s52, s14
	s_cmp_eq_u32 s8, s18
	s_cbranch_scc1 .LBB0_325
	global_load_dwordx4 v[154:157], v[136:137], off nt
	global_load_dwordx4 v[158:161], v[136:137], off offset:16 nt
	global_load_dwordx4 v[162:165], v[136:137], off offset:32 nt
	global_load_dwordx4 v[166:169], v[136:137], off offset:48 nt
	global_load_dwordx4 v[170:173], v[136:137], off offset:64 nt
	global_load_dwordx4 v[174:177], v[136:137], off offset:80 nt
	global_load_dwordx4 v[178:181], v[136:137], off offset:96 nt
	global_load_dwordx4 v[182:185], v[136:137], off offset:112 nt
	v_and_b32_e32 v139, 64, v153
	v_xor_b32_e32 v138, 1, v153
	v_add_u32_e32 v139, 64, v139
	v_cmp_lt_i32_e32 vcc, v138, v139
	s_xor_b32 s59, s64, 1
	s_nop 0
	v_cndmask_b32_e32 v139, v153, v138, vcc
	v_lshlrev_b32_e32 v139, 2, v139
	s_waitcnt vmcnt(7)
	v_add_f32_e32 v138, v154, v155
	v_add_f32_e32 v154, v156, v157
	s_waitcnt vmcnt(6)
	v_add_f32_e32 v155, v158, v159
	v_add_f32_e32 v156, v160, v161
	v_add_f32_e32 v138, v138, v154
	s_waitcnt vmcnt(5)
	v_add_f32_e32 v157, v162, v163
	v_add_f32_e32 v158, v164, v165
	v_add_f32_e32 v154, v155, v156
	v_add_f32_e32 v138, 0, v138
	s_waitcnt vmcnt(4)
	v_add_f32_e32 v159, v166, v167
	v_add_f32_e32 v160, v168, v169
	v_add_f32_e32 v155, v157, v158
	v_add_f32_e32 v138, v138, v154
	s_waitcnt vmcnt(3)
	v_add_f32_e32 v161, v170, v171
	v_add_f32_e32 v162, v172, v173
	v_add_f32_e32 v156, v159, v160
	v_add_f32_e32 v138, v138, v155
	s_waitcnt vmcnt(2)
	v_add_f32_e32 v163, v174, v175
	v_add_f32_e32 v164, v176, v177
	v_add_f32_e32 v157, v161, v162
	v_add_f32_e32 v138, v138, v156
	s_waitcnt vmcnt(1)
	v_add_f32_e32 v165, v178, v179
	v_add_f32_e32 v166, v180, v181
	v_add_f32_e32 v158, v163, v164
	v_add_f32_e32 v138, v138, v157
	s_waitcnt vmcnt(0)
	v_add_f32_e32 v167, v182, v183
	v_add_f32_e32 v168, v184, v185
	v_add_f32_e32 v159, v165, v166
	v_add_f32_e32 v138, v138, v158
	v_add_f32_e32 v160, v167, v168
	v_add_f32_e32 v138, v138, v159
	v_add_f32_e32 v138, v138, v160
	ds_bpermute_b32 v139, v139, v138
	s_and_saveexec_b64 s[60:61], s[0:1]
	s_cbranch_execz .LBB0_324
	s_waitcnt lgkmcnt(0)
	v_add_f32_e32 v138, v138, v139
	v_fmamk_f32 v138, v138, 0x39800000, v149
	s_mov_b32 s8, 0xf800000
	v_mul_f32_e32 v139, 0x4f800000, v138
	v_cmp_gt_f32_e32 vcc, s8, v138
	s_nop 1
	v_cndmask_b32_e32 v138, v138, v139, vcc
	v_sqrt_f32_e32 v139, v138
	s_nop 0
	v_add_u32_e32 v154, -1, v139
	v_fma_f32 v156, -v154, v139, v138
	v_add_u32_e32 v155, 1, v139
	v_cmp_ge_f32_e64 s[8:9], 0, v156
	s_nop 1
	v_cndmask_b32_e64 v154, v139, v154, s[8:9]
	v_fma_f32 v139, -v155, v139, v138
	v_cmp_lt_f32_e64 s[8:9], 0, v139
	s_nop 1
	v_cndmask_b32_e64 v139, v154, v155, s[8:9]
	v_mul_f32_e32 v154, 0x37800000, v139
	v_cndmask_b32_e32 v139, v139, v154, vcc
	v_cmp_class_f32_e32 vcc, v138, v150
	s_nop 1
	v_cndmask_b32_e32 v138, v139, v138, vcc
	v_div_scale_f32 v139, s[8:9], v138, v138, 1.0
	v_rcp_f32_e32 v154, v139
	s_nop 0
	v_fma_f32 v155, -v139, v154, 1.0
	v_fmac_f32_e32 v154, v155, v154
	v_div_scale_f32 v155, vcc, 1.0, v138, 1.0
	v_mul_f32_e32 v156, v155, v154
	v_fma_f32 v157, -v139, v156, v155
	v_fmac_f32_e32 v156, v157, v154
	v_fma_f32 v139, -v139, v156, v155
	v_div_fmas_f32 v139, v139, v154, v156
	v_div_fixup_f32 v138, v139, v138, 1.0
	v_lshl_add_u32 v139, s59, 10, v146
	ds_write_b32 v139, v138

; __device__ __forceinline__ unsigned cvt_pk_bf16(float lo, float hi) { unsigned r; asm volatile("v_cvt_pk_bf16_f32 %0, %1, %2" : "=v"(r) : "v"(lo), "v"(hi)); return r; }
;     __device__ __forceinline__ void operator()(const f32x4 (&acc)[2][2][4][2], const Unit& u, int wr, int wc, int fr, int fq) const {
;     ...
;             for (int m = 0; m < 4; ++m) { const size_t r = (size_t)(row0 + ai * HALF + m * 16); const size_t off = r * ldc + col0; float ss = 0.f;
; #pragma unroll
;                 for (int bj = 0; bj < 2; ++bj) { const f32x4 b0 = *(const f32x4*)(base + off + bj * HALF), b1 = *(const f32x4*)(base + off + bj * HALF + 4);
;                     const f32x4 g0 = *(const f32x4*)(gain + col0 + bj * HALF), g1 = *(const f32x4*)(gain + col0 + bj * HALF + 4);
;                     const f32x4 v0 = b0 + acc[ai][bj][m][0] * alpha, v1 = b1 + acc[ai][bj][m][1] * alpha;
;                     *(f32x4*)(out + off + bj * HALF) = v0; *(f32x4*)(out + off + bj * HALF + 4) = v1;
;                     ss += (v0[0] * v0[0] + v0[1] * v0[1]) + (v0[2] * v0[2] + v0[3] * v0[3]) + (v1[0] * v1[0] + v1[1] * v1[1]) + (v1[2] * v1[2] + v1[3] * v1[3]);
;                     const f32x4 x0 = v0 * g0, x1 = v1 * g1;
;                     u32x4 w; w.x = cvt_pk_bf16(x0[0], x0[1]); w.y = cvt_pk_bf16(x0[2], x0[3]); w.z = cvt_pk_bf16(x1[0], x1[1]); w.w = cvt_pk_bf16(x1[2], x1[3]);
;                     *(u32x4*)(XB + off + bj * HALF) = w; }
;                 ss += __shfl_xor(ss, 16); ss += __shfl_xor(ss, 32);
;                 if (fq == 0) SSQ[r * 64 + u.pn * 4 + wc] = ss; }
.LBB0_701:
	v_lshl_add_u32 v138, s40, 8, v143
	v_lshl_or_b32 v136, s10, 8, v144
	v_ashrrev_i32_e32 v139, 31, v138
	v_ashrrev_i32_e32 v137, 31, v136
	v_lshlrev_b64 v[134:135], 12, v[138:139]
	v_lshl_add_u64 v[168:169], v[134:135], 0, v[136:137]
	v_lshl_add_u64 v[172:173], v[168:169], 2, s[26:27]
	global_load_dwordx4 v[152:155], v[172:173], off nt
	global_load_dwordx4 v[156:159], v[172:173], off offset:16 nt
	v_lshl_add_u64 v[134:135], v[136:137], 2, s[80:81]
	global_load_dwordx4 v[160:163], v[134:135], off
	global_load_dwordx4 v[164:167], v[134:135], off offset:16
	v_lshl_add_u64 v[174:175], v[168:169], 1, s[20:21]
	s_lshl_b32 s40, s10, 2
	s_ashr_i32 s41, s40, 31
	s_waitcnt vmcnt(3)
	v_pk_add_f32 v[128:129], v[128:129], v[154:155]
	v_pk_add_f32 v[126:127], v[126:127], v[152:153]
	s_waitcnt vmcnt(2)
	v_pk_add_f32 v[154:155], v[124:125], v[158:159]
	v_pk_add_f32 v[152:153], v[122:123], v[156:157]
	s_waitcnt vmcnt(1)
	v_pk_mul_f32 v[124:125], v[162:163], v[128:129]
	v_pk_mul_f32 v[122:123], v[160:161], v[126:127]
	global_store_dwordx4 v[172:173], v[126:129], off nt
	global_store_dwordx4 v[172:173], v[152:155], off offset:16 nt
	s_waitcnt vmcnt(2)
	v_pk_mul_f32 v[156:157], v[166:167], v[154:155]
	v_pk_mul_f32 v[158:159], v[164:165], v[152:153]
	v_cvt_pk_bf16_f32 v122, v122, v123
	v_cvt_pk_bf16_f32 v123, v124, v125
	s_nop 0
	v_cvt_pk_bf16_f32 v124, v158, v159
	v_cvt_pk_bf16_f32 v125, v156, v157
	global_store_dwordx4 v[174:175], v[122:125], off
	global_load_dwordx4 v[156:159], v[172:173], off offset:512 nt
	global_load_dwordx4 v[160:163], v[172:173], off offset:528 nt
	global_load_dwordx4 v[164:167], v[134:135], off offset:512
	global_load_dwordx4 v[168:171], v[134:135], off offset:528
	v_and_b32_e32 v123, 64, v150
	v_xor_b32_e32 v122, 16, v150
	v_add_u32_e32 v123, 64, v123
	v_xor_b32_e32 v124, 32, v150
	v_cmp_lt_i32_e32 vcc, v122, v123
	v_mul_f32_e32 v125, v129, v129
	v_fmac_f32_e32 v125, v128, v128
	v_cndmask_b32_e32 v122, v150, v122, vcc
	v_cmp_lt_i32_e32 vcc, v124, v123
	v_mul_f32_e32 v129, v155, v155
	v_fmac_f32_e32 v129, v154, v154
	v_cndmask_b32_e32 v123, v150, v124, vcc
	v_mul_f32_e32 v124, v127, v127
	v_mul_f32_e32 v127, v153, v153
	v_fmac_f32_e32 v124, v126, v126
	v_fmac_f32_e32 v127, v152, v152
	v_add_f32_e32 v124, v124, v125
	v_add_f32_e32 v124, v127, v124
	v_add_f32_e32 v126, v129, v124
	v_lshlrev_b32_e32 v122, 2, v122
	s_waitcnt vmcnt(3)
	v_pk_add_f32 v[120:121], v[120:121], v[158:159]
	v_pk_add_f32 v[118:119], v[118:119], v[156:157]
	s_waitcnt vmcnt(2)
	v_pk_add_f32 v[114:115], v[114:115], v[160:161]
	v_mul_f32_e32 v127, v119, v119
	v_mul_f32_e32 v128, v121, v121
	v_pk_add_f32 v[116:117], v[116:117], v[162:163]
	v_mul_f32_e32 v129, v115, v115
	v_fmac_f32_e32 v127, v118, v118
	v_fmac_f32_e32 v128, v120, v120
	global_store_dwordx4 v[172:173], v[118:121], off offset:512 nt
	global_store_dwordx4 v[172:173], v[114:117], off offset:528 nt
	v_mul_f32_e32 v151, v117, v117
	s_waitcnt vmcnt(3)
	v_pk_mul_f32 v[124:125], v[166:167], v[120:121]
	v_fmac_f32_e32 v129, v114, v114
	v_add_f32_e32 v120, v127, v128
	v_fmac_f32_e32 v151, v116, v116
	v_add_f32_e32 v120, v129, v120
	v_add_f32_e32 v120, v151, v120
	v_add_f32_e32 v128, v126, v120
	ds_bpermute_b32 v129, v122, v128
	s_waitcnt vmcnt(2)
	v_pk_mul_f32 v[126:127], v[170:171], v[116:117]
	v_pk_mul_f32 v[120:121], v[168:169], v[114:115]
	v_lshlrev_b32_e32 v116, 2, v123
	v_pk_mul_f32 v[118:119], v[164:165], v[118:119]
	s_waitcnt lgkmcnt(0)
	v_add_f32_e32 v114, v128, v129
	ds_bpermute_b32 v115, v116, v114
	v_cvt_pk_bf16_f32 v118, v118, v119
	v_cvt_pk_bf16_f32 v119, v124, v125
	v_cvt_pk_bf16_f32 v120, v120, v121
	v_cvt_pk_bf16_f32 v121, v126, v127
	global_store_dwordx4 v[174:175], v[118:121], off offset:256
	s_and_saveexec_b64 s[42:43], s[0:1]
	s_cbranch_execz .LBB0_703
	v_lshlrev_b64 v[118:119], 8, v[138:139]
	v_lshl_add_u64 v[118:119], s[38:39], 0, v[118:119]
	v_lshl_add_u64 v[118:119], s[40:41], 2, v[118:119]
	s_lshl_b32 s10, s60, 2
	v_lshl_add_u64 v[118:119], v[118:119], 0, s[10:11]
	s_waitcnt lgkmcnt(0)
	v_add_f32_e32 v114, v114, v115
	global_store_dword v[118:119], v114, off
.LBB0_703:
	s_or_b64 exec, exec, s[42:43]
	v_or_b32_e32 v114, 16, v138
	s_waitcnt lgkmcnt(0)
	v_ashrrev_i32_e32 v115, 31, v114
	v_lshlrev_b64 v[118:119], 12, v[114:115]
	v_lshl_add_u64 v[128:129], v[118:119], 0, v[136:137]
	v_lshl_add_u64 v[160:161], v[128:129], 2, s[26:27]
	global_load_dwordx4 v[118:121], v[160:161], off nt
	global_load_dwordx4 v[124:127], v[160:161], off offset:16 nt
	global_load_dwordx4 v[152:155], v[134:135], off
	global_load_dwordx4 v[156:159], v[134:135], off offset:16
	v_lshl_add_u64 v[128:129], v[128:129], 1, s[20:21]
	s_waitcnt vmcnt(3)
	v_pk_add_f32 v[112:113], v[112:113], v[120:121]
	v_pk_add_f32 v[110:111], v[110:111], v[118:119]
	s_waitcnt vmcnt(2)
	v_pk_add_f32 v[108:109], v[108:109], v[126:127]
	v_pk_add_f32 v[106:107], v[106:107], v[124:125]
	s_waitcnt vmcnt(1)
	v_pk_mul_f32 v[120:121], v[154:155], v[112:113]
	v_pk_mul_f32 v[118:119], v[152:153], v[110:111]
	global_store_dwordx4 v[160:161], v[110:113], off nt
	global_store_dwordx4 v[160:161], v[106:109], off offset:16 nt
	s_waitcnt vmcnt(2)
	v_pk_mul_f32 v[124:125], v[158:159], v[108:109]
	v_pk_mul_f32 v[126:127], v[156:157], v[106:107]
	v_cvt_pk_bf16_f32 v118, v118, v119
	v_cvt_pk_bf16_f32 v119, v120, v121
	v_mul_f32_e32 v111, v111, v111
	v_cvt_pk_bf16_f32 v120, v126, v127
	v_cvt_pk_bf16_f32 v121, v124, v125
	global_store_dwordx4 v[128:129], v[118:121], off
	global_load_dwordx4 v[118:121], v[160:161], off offset:512
	s_nop 0
	global_load_dwordx4 v[124:127], v[160:161], off offset:528
	global_load_dwordx4 v[152:155], v[134:135], off offset:512
	global_load_dwordx4 v[156:159], v[134:135], off offset:528
	v_mul_f32_e32 v113, v113, v113
	v_mul_f32_e32 v107, v107, v107
	v_fmac_f32_e32 v111, v110, v110
	v_fmac_f32_e32 v113, v112, v112
	v_mul_f32_e32 v109, v109, v109
	v_fmac_f32_e32 v107, v106, v106
	v_add_f32_e32 v106, v111, v113
	v_fmac_f32_e32 v109, v108, v108
	v_add_f32_e32 v106, v107, v106
	v_add_f32_e32 v106, v109, v106
	s_waitcnt vmcnt(3)
; __device__ __forceinline__ unsigned cvt_pk_bf16(float lo, float hi) { unsigned r; asm volatile("v_cvt_pk_bf16_f32 %0, %1, %2" : "=v"(r) : "v"(lo), "v"(hi)); return r; }
;     __device__ __forceinline__ void operator()(const f32x4 (&acc)[2][2][4][2], const Unit& u, int wr, int wc, int fr, int fq) const {
;     ...
;             for (int m = 0; m < 4; ++m) { const size_t r = (size_t)(row0 + ai * HALF + m * 16); const size_t off = r * ldc + col0; float ss = 0.f;
; #pragma unroll
;                 for (int bj = 0; bj < 2; ++bj) { const f32x4 b0 = *(const f32x4*)(base + off + bj * HALF), b1 = *(const f32x4*)(base + off + bj * HALF + 4);
;                     const f32x4 g0 = *(const f32x4*)(gain + col0 + bj * HALF), g1 = *(const f32x4*)(gain + col0 + bj * HALF + 4);
;                     const f32x4 v0 = b0 + acc[ai][bj][m][0] * alpha, v1 = b1 + acc[ai][bj][m][1] * alpha;
;                     *(f32x4*)(out + off + bj * HALF) = v0; *(f32x4*)(out + off + bj * HALF + 4) = v1;
;                     ss += (v0[0] * v0[0] + v0[1] * v0[1]) + (v0[2] * v0[2] + v0[3] * v0[3]) + (v1[0] * v1[0] + v1[1] * v1[1]) + (v1[2] * v1[2] + v1[3] * v1[3]);
;                     const f32x4 x0 = v0 * g0, x1 = v1 * g1;
;                     u32x4 w; w.x = cvt_pk_bf16(x0[0], x0[1]); w.y = cvt_pk_bf16(x0[2], x0[3]); w.z = cvt_pk_bf16(x1[0], x1[1]); w.w = cvt_pk_bf16(x1[2], x1[3]);
;                     *(u32x4*)(XB + off + bj * HALF) = w; }
;                 ss += __shfl_xor(ss, 16); ss += __shfl_xor(ss, 32);
;                 if (fq == 0) SSQ[r * 64 + u.pn * 4 + wc] = ss; }
	v_pk_add_f32 v[104:105], v[104:105], v[120:121]
	v_pk_add_f32 v[102:103], v[102:103], v[118:119]
	s_waitcnt vmcnt(2)
	v_pk_add_f32 v[98:99], v[98:99], v[124:125]
	v_mul_f32_e32 v107, v103, v103
	v_mul_f32_e32 v108, v105, v105
	v_pk_add_f32 v[100:101], v[100:101], v[126:127]
	v_mul_f32_e32 v109, v99, v99
	v_fmac_f32_e32 v107, v102, v102
	v_fmac_f32_e32 v108, v104, v104
	v_mul_f32_e32 v110, v101, v101
	v_fmac_f32_e32 v109, v98, v98
	v_add_f32_e32 v107, v107, v108
	v_fmac_f32_e32 v110, v100, v100
	v_add_f32_e32 v107, v109, v107
	v_add_f32_e32 v107, v110, v107
	v_add_f32_e32 v110, v106, v107
	ds_bpermute_b32 v111, v122, v110
	global_store_dwordx4 v[160:161], v[102:105], off offset:512 nt
	global_store_dwordx4 v[160:161], v[98:101], off offset:528 nt
	s_waitcnt vmcnt(2)
	v_pk_mul_f32 v[108:109], v[156:157], v[98:99]
	v_pk_mul_f32 v[102:103], v[152:153], v[102:103]
	v_pk_mul_f32 v[104:105], v[154:155], v[104:105]
	s_waitcnt lgkmcnt(0)
	v_add_f32_e32 v98, v110, v111
	ds_bpermute_b32 v99, v116, v98
	v_pk_mul_f32 v[106:107], v[158:159], v[100:101]
	v_cvt_pk_bf16_f32 v100, v102, v103
	v_cvt_pk_bf16_f32 v101, v104, v105
	v_cvt_pk_bf16_f32 v102, v108, v109
	s_nop 0
	v_cvt_pk_bf16_f32 v103, v106, v107
	global_store_dwordx4 v[128:129], v[100:103], off offset:256
	s_and_saveexec_b64 s[42:43], s[0:1]
	s_cbranch_execz .LBB0_705
	v_lshlrev_b64 v[100:101], 8, v[114:115]
	v_lshl_add_u64 v[100:101], s[38:39], 0, v[100:101]
	v_lshl_add_u64 v[100:101], s[40:41], 2, v[100:101]
	s_lshl_b32 s10, s60, 2
	v_lshl_add_u64 v[100:101], v[100:101], 0, s[10:11]
	s_waitcnt lgkmcnt(0)
	v_add_f32_e32 v98, v98, v99
	global_store_dword v[100:101], v98, off
.LBB0_705:
	s_or_b64 exec, exec, s[42:43]
	v_or_b32_e32 v98, 32, v138
	s_waitcnt lgkmcnt(0)
	v_ashrrev_i32_e32 v99, 31, v98
	v_lshlrev_b64 v[100:101], 12, v[98:99]
	v_lshl_add_u64 v[118:119], v[100:101], 0, v[136:137]
	v_lshl_add_u64 v[120:121], v[118:119], 2, s[26:27]
	global_load_dwordx4 v[100:103], v[120:121], off nt
	global_load_dwordx4 v[104:107], v[120:121], off offset:16 nt
	global_load_dwordx4 v[108:111], v[134:135], off
	global_load_dwordx4 v[112:115], v[134:135], off offset:16
	v_lshl_add_u64 v[118:119], v[118:119], 1, s[20:21]
	s_waitcnt vmcnt(3)
	v_pk_add_f32 v[96:97], v[96:97], v[102:103]
	v_pk_add_f32 v[94:95], v[94:95], v[100:101]
	s_waitcnt vmcnt(2)
	v_pk_add_f32 v[92:93], v[92:93], v[106:107]
	v_pk_add_f32 v[90:91], v[90:91], v[104:105]
	s_waitcnt vmcnt(1)
	v_pk_mul_f32 v[102:103], v[110:111], v[96:97]
	v_pk_mul_f32 v[100:101], v[108:109], v[94:95]
	global_store_dwordx4 v[120:121], v[94:97], off nt
	global_store_dwordx4 v[120:121], v[90:93], off offset:16 nt
	s_waitcnt vmcnt(2)
	v_pk_mul_f32 v[104:105], v[114:115], v[92:93]
	v_pk_mul_f32 v[106:107], v[112:113], v[90:91]
	v_cvt_pk_bf16_f32 v100, v100, v101
	v_cvt_pk_bf16_f32 v101, v102, v103
	v_mul_f32_e32 v95, v95, v95
	v_cvt_pk_bf16_f32 v102, v106, v107
	v_cvt_pk_bf16_f32 v103, v104, v105
	global_store_dwordx4 v[118:119], v[100:103], off
	global_load_dwordx4 v[100:103], v[120:121], off offset:512
	s_nop 0
	global_load_dwordx4 v[104:107], v[120:121], off offset:528
	global_load_dwordx4 v[108:111], v[134:135], off offset:512
	global_load_dwordx4 v[112:115], v[134:135], off offset:528
	v_mul_f32_e32 v97, v97, v97
	v_mul_f32_e32 v91, v91, v91
	v_fmac_f32_e32 v95, v94, v94
	v_fmac_f32_e32 v97, v96, v96
	v_mul_f32_e32 v93, v93, v93
	v_fmac_f32_e32 v91, v90, v90
	v_add_f32_e32 v90, v95, v97
	v_fmac_f32_e32 v93, v92, v92
	v_add_f32_e32 v90, v91, v90
	v_add_f32_e32 v90, v93, v90
	s_waitcnt vmcnt(3)
	v_pk_add_f32 v[88:89], v[88:89], v[102:103]
	v_pk_add_f32 v[86:87], v[86:87], v[100:101]
	s_waitcnt vmcnt(2)
	v_pk_add_f32 v[82:83], v[82:83], v[104:105]
	v_mul_f32_e32 v91, v87, v87
	v_mul_f32_e32 v92, v89, v89
	v_pk_add_f32 v[84:85], v[84:85], v[106:107]
	v_mul_f32_e32 v93, v83, v83
	v_fmac_f32_e32 v91, v86, v86
	v_fmac_f32_e32 v92, v88, v88
	v_mul_f32_e32 v94, v85, v85
	v_fmac_f32_e32 v93, v82, v82
	v_add_f32_e32 v91, v91, v92
	v_fmac_f32_e32 v94, v84, v84
	v_add_f32_e32 v91, v93, v91
	v_add_f32_e32 v91, v94, v91
	v_add_f32_e32 v94, v90, v91
	ds_bpermute_b32 v95, v122, v94
	global_store_dwordx4 v[120:121], v[86:89], off offset:512 nt
	global_store_dwordx4 v[120:121], v[82:85], off offset:528 nt
	s_waitcnt vmcnt(2)
	v_pk_mul_f32 v[92:93], v[112:113], v[82:83]
	v_pk_mul_f32 v[86:87], v[108:109], v[86:87]
	v_pk_mul_f32 v[88:89], v[110:111], v[88:89]
	s_waitcnt lgkmcnt(0)
	v_add_f32_e32 v82, v94, v95
	ds_bpermute_b32 v83, v116, v82
	v_pk_mul_f32 v[90:91], v[114:115], v[84:85]
	v_cvt_pk_bf16_f32 v84, v86, v87
	v_cvt_pk_bf16_f32 v85, v88, v89
	v_cvt_pk_bf16_f32 v86, v92, v93
	s_nop 0
	v_cvt_pk_bf16_f32 v87, v90, v91
	global_store_dwordx4 v[118:119], v[84:87], off offset:256
	s_and_saveexec_b64 s[42:43], s[0:1]
	s_cbranch_execz .LBB0_707
	v_lshlrev_b64 v[84:85], 8, v[98:99]
	v_lshl_add_u64 v[84:85], s[38:39], 0, v[84:85]
	v_lshl_add_u64 v[84:85], s[40:41], 2, v[84:85]
	s_lshl_b32 s10, s60, 2
	v_lshl_add_u64 v[84:85], v[84:85], 0, s[10:11]
	s_waitcnt lgkmcnt(0)
	v_add_f32_e32 v82, v82, v83
	global_store_dword v[84:85], v82, off
; __device__ __forceinline__ unsigned cvt_pk_bf16(float lo, float hi) { unsigned r; asm volatile("v_cvt_pk_bf16_f32 %0, %1, %2" : "=v"(r) : "v"(lo), "v"(hi)); return r; }
;     __device__ __forceinline__ void operator()(const f32x4 (&acc)[2][2][4][2], const Unit& u, int wr, int wc, int fr, int fq) const {
;     ...
;             for (int m = 0; m < 4; ++m) { const size_t r = (size_t)(row0 + ai * HALF + m * 16); const size_t off = r * ldc + col0; float ss = 0.f;
; #pragma unroll
;                 for (int bj = 0; bj < 2; ++bj) { const f32x4 b0 = *(const f32x4*)(base + off + bj * HALF), b1 = *(const f32x4*)(base + off + bj * HALF + 4);
;                     const f32x4 g0 = *(const f32x4*)(gain + col0 + bj * HALF), g1 = *(const f32x4*)(gain + col0 + bj * HALF + 4);
;                     const f32x4 v0 = b0 + acc[ai][bj][m][0] * alpha, v1 = b1 + acc[ai][bj][m][1] * alpha;
;                     *(f32x4*)(out + off + bj * HALF) = v0; *(f32x4*)(out + off + bj * HALF + 4) = v1;
;                     ss += (v0[0] * v0[0] + v0[1] * v0[1]) + (v0[2] * v0[2] + v0[3] * v0[3]) + (v1[0] * v1[0] + v1[1] * v1[1]) + (v1[2] * v1[2] + v1[3] * v1[3]);
;                     const f32x4 x0 = v0 * g0, x1 = v1 * g1;
;                     u32x4 w; w.x = cvt_pk_bf16(x0[0], x0[1]); w.y = cvt_pk_bf16(x0[2], x0[3]); w.z = cvt_pk_bf16(x1[0], x1[1]); w.w = cvt_pk_bf16(x1[2], x1[3]);
;                     *(u32x4*)(XB + off + bj * HALF) = w; }
;                 ss += __shfl_xor(ss, 16); ss += __shfl_xor(ss, 32);
;                 if (fq == 0) SSQ[r * 64 + u.pn * 4 + wc] = ss; }
.LBB0_707:
	s_or_b64 exec, exec, s[42:43]
	v_or_b32_e32 v82, 48, v138
	s_waitcnt lgkmcnt(0)
	v_ashrrev_i32_e32 v83, 31, v82
	v_lshlrev_b64 v[84:85], 12, v[82:83]
	v_lshl_add_u64 v[100:101], v[84:85], 0, v[136:137]
	v_lshl_add_u64 v[102:103], v[100:101], 2, s[26:27]
	global_load_dwordx4 v[84:87], v[102:103], off nt
	global_load_dwordx4 v[88:91], v[102:103], off offset:16 nt
	global_load_dwordx4 v[92:95], v[134:135], off
	global_load_dwordx4 v[96:99], v[134:135], off offset:16
	v_lshl_add_u64 v[100:101], v[100:101], 1, s[20:21]
	s_waitcnt vmcnt(3)
	v_pk_add_f32 v[80:81], v[80:81], v[86:87]
	v_pk_add_f32 v[78:79], v[78:79], v[84:85]
	s_waitcnt vmcnt(2)
	v_pk_add_f32 v[76:77], v[76:77], v[90:91]
	v_pk_add_f32 v[74:75], v[74:75], v[88:89]
	s_waitcnt vmcnt(1)
	v_pk_mul_f32 v[86:87], v[94:95], v[80:81]
	v_pk_mul_f32 v[84:85], v[92:93], v[78:79]
	global_store_dwordx4 v[102:103], v[78:81], off nt
	global_store_dwordx4 v[102:103], v[74:77], off offset:16 nt
	s_waitcnt vmcnt(2)
	v_pk_mul_f32 v[88:89], v[98:99], v[76:77]
	v_pk_mul_f32 v[90:91], v[96:97], v[74:75]
	v_cvt_pk_bf16_f32 v84, v84, v85
	v_cvt_pk_bf16_f32 v85, v86, v87
	v_mul_f32_e32 v79, v79, v79
	v_cvt_pk_bf16_f32 v86, v90, v91
	v_cvt_pk_bf16_f32 v87, v88, v89
	global_store_dwordx4 v[100:101], v[84:87], off
	global_load_dwordx4 v[84:87], v[102:103], off offset:512
	s_nop 0
	global_load_dwordx4 v[88:91], v[102:103], off offset:528
	global_load_dwordx4 v[92:95], v[134:135], off offset:512
	global_load_dwordx4 v[96:99], v[134:135], off offset:528
	v_mul_f32_e32 v81, v81, v81
	v_mul_f32_e32 v75, v75, v75
	v_fmac_f32_e32 v79, v78, v78
	v_fmac_f32_e32 v81, v80, v80
	v_mul_f32_e32 v77, v77, v77
	v_fmac_f32_e32 v75, v74, v74
	v_add_f32_e32 v74, v79, v81
	v_fmac_f32_e32 v77, v76, v76
	v_add_f32_e32 v74, v75, v74
	v_add_f32_e32 v74, v77, v74
	s_waitcnt vmcnt(3)
	v_pk_add_f32 v[72:73], v[72:73], v[86:87]
	v_pk_add_f32 v[70:71], v[70:71], v[84:85]
	s_waitcnt vmcnt(2)
	v_pk_add_f32 v[66:67], v[66:67], v[88:89]
	v_mul_f32_e32 v75, v71, v71
	v_mul_f32_e32 v76, v73, v73
	v_pk_add_f32 v[68:69], v[68:69], v[90:91]
	v_mul_f32_e32 v77, v67, v67
	v_fmac_f32_e32 v75, v70, v70
	v_fmac_f32_e32 v76, v72, v72
	v_mul_f32_e32 v78, v69, v69
	v_fmac_f32_e32 v77, v66, v66
	v_add_f32_e32 v75, v75, v76
	v_fmac_f32_e32 v78, v68, v68
	v_add_f32_e32 v75, v77, v75
	v_add_f32_e32 v75, v78, v75
	v_add_f32_e32 v78, v74, v75
	ds_bpermute_b32 v79, v122, v78
	global_store_dwordx4 v[102:103], v[70:73], off offset:512 nt
	global_store_dwordx4 v[102:103], v[66:69], off offset:528 nt
	s_waitcnt vmcnt(2)
	v_pk_mul_f32 v[76:77], v[96:97], v[66:67]
	v_pk_mul_f32 v[70:71], v[92:93], v[70:71]
	v_pk_mul_f32 v[72:73], v[94:95], v[72:73]
	s_waitcnt lgkmcnt(0)
	v_add_f32_e32 v66, v78, v79
	ds_bpermute_b32 v67, v116, v66
	v_pk_mul_f32 v[74:75], v[98:99], v[68:69]
	v_cvt_pk_bf16_f32 v68, v70, v71
	v_cvt_pk_bf16_f32 v69, v72, v73
	v_cvt_pk_bf16_f32 v70, v76, v77
	s_nop 0
	v_cvt_pk_bf16_f32 v71, v74, v75
	global_store_dwordx4 v[100:101], v[68:71], off offset:256
	s_and_saveexec_b64 s[42:43], s[0:1]
	s_cbranch_execz .LBB0_709
	v_lshlrev_b64 v[68:69], 8, v[82:83]
	v_lshl_add_u64 v[68:69], s[38:39], 0, v[68:69]
	v_lshl_add_u64 v[68:69], s[40:41], 2, v[68:69]
	s_lshl_b32 s10, s60, 2
	v_lshl_add_u64 v[68:69], v[68:69], 0, s[10:11]
	s_waitcnt lgkmcnt(0)
	v_add_f32_e32 v66, v66, v67
	global_store_dword v[68:69], v66, off
.LBB0_709:
	s_or_b64 exec, exec, s[42:43]
	v_add_u32_e32 v66, 0x80, v138
	s_waitcnt lgkmcnt(0)
	v_ashrrev_i32_e32 v67, 31, v66
	v_lshlrev_b64 v[68:69], 12, v[66:67]
	v_lshl_add_u64 v[84:85], v[68:69], 0, v[136:137]
	v_lshl_add_u64 v[86:87], v[84:85], 2, s[26:27]
	global_load_dwordx4 v[68:71], v[86:87], off nt
	global_load_dwordx4 v[72:75], v[86:87], off offset:16 nt
	global_load_dwordx4 v[76:79], v[134:135], off
	global_load_dwordx4 v[80:83], v[134:135], off offset:16
	v_lshl_add_u64 v[84:85], v[84:85], 1, s[20:21]
	s_waitcnt vmcnt(3)
	v_pk_add_f32 v[64:65], v[64:65], v[70:71]
	v_pk_add_f32 v[62:63], v[62:63], v[68:69]
	s_waitcnt vmcnt(2)
	v_pk_add_f32 v[60:61], v[60:61], v[74:75]
	v_pk_add_f32 v[58:59], v[58:59], v[72:73]
	s_waitcnt vmcnt(1)
	v_pk_mul_f32 v[70:71], v[78:79], v[64:65]
	v_pk_mul_f32 v[68:69], v[76:77], v[62:63]
	global_store_dwordx4 v[86:87], v[62:65], off nt
	global_store_dwordx4 v[86:87], v[58:61], off offset:16 nt
	s_waitcnt vmcnt(2)
	v_pk_mul_f32 v[72:73], v[82:83], v[60:61]
	v_pk_mul_f32 v[74:75], v[80:81], v[58:59]
	v_cvt_pk_bf16_f32 v68, v68, v69
	v_cvt_pk_bf16_f32 v69, v70, v71
	v_mul_f32_e32 v63, v63, v63
	v_cvt_pk_bf16_f32 v70, v74, v75
	v_cvt_pk_bf16_f32 v71, v72, v73
	global_store_dwordx4 v[84:85], v[68:71], off
	global_load_dwordx4 v[68:71], v[86:87], off offset:512
	s_nop 0
	global_load_dwordx4 v[72:75], v[86:87], off offset:528
	global_load_dwordx4 v[76:79], v[134:135], off offset:512
	global_load_dwordx4 v[80:83], v[134:135], off offset:528
	v_mul_f32_e32 v65, v65, v65
	v_mul_f32_e32 v59, v59, v59
	v_fmac_f32_e32 v63, v62, v62
	v_fmac_f32_e32 v65, v64, v64
	v_mul_f32_e32 v61, v61, v61
	v_fmac_f32_e32 v59, v58, v58
	v_add_f32_e32 v58, v63, v65
	v_fmac_f32_e32 v61, v60, v60
	v_add_f32_e32 v58, v59, v58
	v_add_f32_e32 v58, v61, v58
	s_waitcnt vmcnt(3)
	v_pk_add_f32 v[56:57], v[56:57], v[70:71]
	v_pk_add_f32 v[54:55], v[54:55], v[68:69]
	s_waitcnt vmcnt(2)
	v_pk_add_f32 v[50:51], v[50:51], v[72:73]
	v_mul_f32_e32 v59, v55, v55
	v_mul_f32_e32 v60, v57, v57
	v_pk_add_f32 v[52:53], v[52:53], v[74:75]
	v_mul_f32_e32 v61, v51, v51
	v_fmac_f32_e32 v59, v54, v54
	v_fmac_f32_e32 v60, v56, v56
	v_mul_f32_e32 v62, v53, v53
	v_fmac_f32_e32 v61, v50, v50
	v_add_f32_e32 v59, v59, v60
	v_fmac_f32_e32 v62, v52, v52
	v_add_f32_e32 v59, v61, v59
	v_add_f32_e32 v59, v62, v59
	v_add_f32_e32 v62, v58, v59
	ds_bpermute_b32 v63, v122, v62
	global_store_dwordx4 v[86:87], v[54:57], off offset:512 nt
	global_store_dwordx4 v[86:87], v[50:53], off offset:528 nt
	s_waitcnt vmcnt(2)
	v_pk_mul_f32 v[60:61], v[80:81], v[50:51]
	v_pk_mul_f32 v[54:55], v[76:77], v[54:55]
	v_pk_mul_f32 v[56:57], v[78:79], v[56:57]
	s_waitcnt lgkmcnt(0)
	v_add_f32_e32 v50, v62, v63
	ds_bpermute_b32 v51, v116, v50
	v_pk_mul_f32 v[58:59], v[82:83], v[52:53]
	v_cvt_pk_bf16_f32 v52, v54, v55
	v_cvt_pk_bf16_f32 v53, v56, v57
	v_cvt_pk_bf16_f32 v54, v60, v61
	s_nop 0
	v_cvt_pk_bf16_f32 v55, v58, v59
	global_store_dwordx4 v[84:85], v[52:55], off offset:256
	s_and_saveexec_b64 s[42:43], s[0:1]
	s_cbranch_execz .LBB0_711
	v_lshlrev_b64 v[52:53], 8, v[66:67]
	v_lshl_add_u64 v[52:53], s[38:39], 0, v[52:53]
	v_lshl_add_u64 v[52:53], s[40:41], 2, v[52:53]
	s_lshl_b32 s10, s60, 2
	v_lshl_add_u64 v[52:53], v[52:53], 0, s[10:11]
	s_waitcnt lgkmcnt(0)
	v_add_f32_e32 v50, v50, v51
	global_store_dword v[52:53], v50, off
; __device__ __forceinline__ unsigned cvt_pk_bf16(float lo, float hi) { unsigned r; asm volatile("v_cvt_pk_bf16_f32 %0, %1, %2" : "=v"(r) : "v"(lo), "v"(hi)); return r; }
;     __device__ __forceinline__ void operator()(const f32x4 (&acc)[2][2][4][2], const Unit& u, int wr, int wc, int fr, int fq) const {
;     ...
;             for (int m = 0; m < 4; ++m) { const size_t r = (size_t)(row0 + ai * HALF + m * 16); const size_t off = r * ldc + col0; float ss = 0.f;
; #pragma unroll
;                 for (int bj = 0; bj < 2; ++bj) { const f32x4 b0 = *(const f32x4*)(base + off + bj * HALF), b1 = *(const f32x4*)(base + off + bj * HALF + 4);
;                     const f32x4 g0 = *(const f32x4*)(gain + col0 + bj * HALF), g1 = *(const f32x4*)(gain + col0 + bj * HALF + 4);
;                     const f32x4 v0 = b0 + acc[ai][bj][m][0] * alpha, v1 = b1 + acc[ai][bj][m][1] * alpha;
;                     *(f32x4*)(out + off + bj * HALF) = v0; *(f32x4*)(out + off + bj * HALF + 4) = v1;
;                     ss += (v0[0] * v0[0] + v0[1] * v0[1]) + (v0[2] * v0[2] + v0[3] * v0[3]) + (v1[0] * v1[0] + v1[1] * v1[1]) + (v1[2] * v1[2] + v1[3] * v1[3]);
;                     const f32x4 x0 = v0 * g0, x1 = v1 * g1;
;                     u32x4 w; w.x = cvt_pk_bf16(x0[0], x0[1]); w.y = cvt_pk_bf16(x0[2], x0[3]); w.z = cvt_pk_bf16(x1[0], x1[1]); w.w = cvt_pk_bf16(x1[2], x1[3]);
;                     *(u32x4*)(XB + off + bj * HALF) = w; }
;                 ss += __shfl_xor(ss, 16); ss += __shfl_xor(ss, 32);
;                 if (fq == 0) SSQ[r * 64 + u.pn * 4 + wc] = ss; }
.LBB0_711:
	s_or_b64 exec, exec, s[42:43]
	v_add_u32_e32 v50, 0x90, v138
	s_waitcnt lgkmcnt(0)
	v_ashrrev_i32_e32 v51, 31, v50
	v_lshlrev_b64 v[52:53], 12, v[50:51]
	v_lshl_add_u64 v[68:69], v[52:53], 0, v[136:137]
	v_lshl_add_u64 v[70:71], v[68:69], 2, s[26:27]
	global_load_dwordx4 v[52:55], v[70:71], off nt
	global_load_dwordx4 v[56:59], v[70:71], off offset:16 nt
	global_load_dwordx4 v[60:63], v[134:135], off
	global_load_dwordx4 v[64:67], v[134:135], off offset:16
	v_lshl_add_u64 v[68:69], v[68:69], 1, s[20:21]
	s_waitcnt vmcnt(3)
	v_pk_add_f32 v[48:49], v[48:49], v[54:55]
	v_pk_add_f32 v[46:47], v[46:47], v[52:53]
	s_waitcnt vmcnt(2)
	v_pk_add_f32 v[44:45], v[44:45], v[58:59]
	v_pk_add_f32 v[42:43], v[42:43], v[56:57]
	s_waitcnt vmcnt(1)
	v_pk_mul_f32 v[54:55], v[62:63], v[48:49]
	v_pk_mul_f32 v[52:53], v[60:61], v[46:47]
	global_store_dwordx4 v[70:71], v[46:49], off nt
	global_store_dwordx4 v[70:71], v[42:45], off offset:16 nt
	s_waitcnt vmcnt(2)
	v_pk_mul_f32 v[56:57], v[66:67], v[44:45]
	v_pk_mul_f32 v[58:59], v[64:65], v[42:43]
	v_cvt_pk_bf16_f32 v52, v52, v53
	v_cvt_pk_bf16_f32 v53, v54, v55
	v_mul_f32_e32 v47, v47, v47
	v_cvt_pk_bf16_f32 v54, v58, v59
	v_cvt_pk_bf16_f32 v55, v56, v57
	global_store_dwordx4 v[68:69], v[52:55], off
	global_load_dwordx4 v[52:55], v[70:71], off offset:512
	s_nop 0
	global_load_dwordx4 v[56:59], v[70:71], off offset:528
	global_load_dwordx4 v[60:63], v[134:135], off offset:512
	global_load_dwordx4 v[64:67], v[134:135], off offset:528
	v_mul_f32_e32 v49, v49, v49
	v_mul_f32_e32 v43, v43, v43
	v_fmac_f32_e32 v47, v46, v46
	v_fmac_f32_e32 v49, v48, v48
	v_mul_f32_e32 v45, v45, v45
	v_fmac_f32_e32 v43, v42, v42
	v_add_f32_e32 v42, v47, v49
	v_fmac_f32_e32 v45, v44, v44
	v_add_f32_e32 v42, v43, v42
	v_add_f32_e32 v42, v45, v42
	s_waitcnt vmcnt(3)
	v_pk_add_f32 v[40:41], v[40:41], v[54:55]
	v_pk_add_f32 v[38:39], v[38:39], v[52:53]
	s_waitcnt vmcnt(2)
	v_pk_add_f32 v[34:35], v[34:35], v[56:57]
	v_mul_f32_e32 v43, v39, v39
	v_mul_f32_e32 v44, v41, v41
	v_pk_add_f32 v[36:37], v[36:37], v[58:59]
	v_mul_f32_e32 v45, v35, v35
	v_fmac_f32_e32 v43, v38, v38
	v_fmac_f32_e32 v44, v40, v40
	v_mul_f32_e32 v46, v37, v37
	v_fmac_f32_e32 v45, v34, v34
	v_add_f32_e32 v43, v43, v44
	v_fmac_f32_e32 v46, v36, v36
	v_add_f32_e32 v43, v45, v43
	v_add_f32_e32 v43, v46, v43
	v_add_f32_e32 v46, v42, v43
	ds_bpermute_b32 v47, v122, v46
	global_store_dwordx4 v[70:71], v[38:41], off offset:512 nt
	global_store_dwordx4 v[70:71], v[34:37], off offset:528 nt
	s_waitcnt vmcnt(2)
	v_pk_mul_f32 v[44:45], v[64:65], v[34:35]
	v_pk_mul_f32 v[38:39], v[60:61], v[38:39]
	v_pk_mul_f32 v[40:41], v[62:63], v[40:41]
	s_waitcnt lgkmcnt(0)
	v_add_f32_e32 v34, v46, v47
	ds_bpermute_b32 v35, v116, v34
	v_pk_mul_f32 v[42:43], v[66:67], v[36:37]
	v_cvt_pk_bf16_f32 v36, v38, v39
	v_cvt_pk_bf16_f32 v37, v40, v41
	v_cvt_pk_bf16_f32 v38, v44, v45
	s_nop 0
	v_cvt_pk_bf16_f32 v39, v42, v43
	global_store_dwordx4 v[68:69], v[36:39], off offset:256
	s_and_saveexec_b64 s[42:43], s[0:1]
	s_cbranch_execz .LBB0_713
	v_lshlrev_b64 v[36:37], 8, v[50:51]
	v_lshl_add_u64 v[36:37], s[38:39], 0, v[36:37]
	v_lshl_add_u64 v[36:37], s[40:41], 2, v[36:37]
	s_lshl_b32 s10, s60, 2
	v_lshl_add_u64 v[36:37], v[36:37], 0, s[10:11]
	s_waitcnt lgkmcnt(0)
	v_add_f32_e32 v34, v34, v35
	global_store_dword v[36:37], v34, off
; __device__ __forceinline__ unsigned cvt_pk_bf16(float lo, float hi) { unsigned r; asm volatile("v_cvt_pk_bf16_f32 %0, %1, %2" : "=v"(r) : "v"(lo), "v"(hi)); return r; }
;     __device__ __forceinline__ void operator()(const f32x4 (&acc)[2][2][4][2], const Unit& u, int wr, int wc, int fr, int fq) const {
;     ...
;             for (int m = 0; m < 4; ++m) { const size_t r = (size_t)(row0 + ai * HALF + m * 16); const size_t off = r * ldc + col0; float ss = 0.f;
; #pragma unroll
;                 for (int bj = 0; bj < 2; ++bj) { const f32x4 b0 = *(const f32x4*)(base + off + bj * HALF), b1 = *(const f32x4*)(base + off + bj * HALF + 4);
;                     const f32x4 g0 = *(const f32x4*)(gain + col0 + bj * HALF), g1 = *(const f32x4*)(gain + col0 + bj * HALF + 4);
;                     const f32x4 v0 = b0 + acc[ai][bj][m][0] * alpha, v1 = b1 + acc[ai][bj][m][1] * alpha;
;                     *(f32x4*)(out + off + bj * HALF) = v0; *(f32x4*)(out + off + bj * HALF + 4) = v1;
;                     ss += (v0[0] * v0[0] + v0[1] * v0[1]) + (v0[2] * v0[2] + v0[3] * v0[3]) + (v1[0] * v1[0] + v1[1] * v1[1]) + (v1[2] * v1[2] + v1[3] * v1[3]);
;                     const f32x4 x0 = v0 * g0, x1 = v1 * g1;
;                     u32x4 w; w.x = cvt_pk_bf16(x0[0], x0[1]); w.y = cvt_pk_bf16(x0[2], x0[3]); w.z = cvt_pk_bf16(x1[0], x1[1]); w.w = cvt_pk_bf16(x1[2], x1[3]);
;                     *(u32x4*)(XB + off + bj * HALF) = w; }
;                 ss += __shfl_xor(ss, 16); ss += __shfl_xor(ss, 32);
;                 if (fq == 0) SSQ[r * 64 + u.pn * 4 + wc] = ss; }
.LBB0_713:
	s_or_b64 exec, exec, s[42:43]
	v_add_u32_e32 v34, 0xa0, v138
	s_waitcnt lgkmcnt(0)
	v_ashrrev_i32_e32 v35, 31, v34
	v_lshlrev_b64 v[36:37], 12, v[34:35]
	v_lshl_add_u64 v[52:53], v[36:37], 0, v[136:137]
	v_lshl_add_u64 v[54:55], v[52:53], 2, s[26:27]
	global_load_dwordx4 v[36:39], v[54:55], off nt
	global_load_dwordx4 v[40:43], v[54:55], off offset:16 nt
	global_load_dwordx4 v[44:47], v[134:135], off
	global_load_dwordx4 v[48:51], v[134:135], off offset:16
	v_lshl_add_u64 v[52:53], v[52:53], 1, s[20:21]
	s_waitcnt vmcnt(3)
	v_pk_add_f32 v[32:33], v[32:33], v[38:39]
	v_pk_add_f32 v[30:31], v[30:31], v[36:37]
	s_waitcnt vmcnt(2)
	v_pk_add_f32 v[28:29], v[28:29], v[42:43]
	v_pk_add_f32 v[26:27], v[26:27], v[40:41]
	s_waitcnt vmcnt(1)
	v_pk_mul_f32 v[38:39], v[46:47], v[32:33]
	v_pk_mul_f32 v[36:37], v[44:45], v[30:31]
	global_store_dwordx4 v[54:55], v[30:33], off nt
	global_store_dwordx4 v[54:55], v[26:29], off offset:16 nt
	s_waitcnt vmcnt(2)
	v_pk_mul_f32 v[40:41], v[50:51], v[28:29]
	v_pk_mul_f32 v[42:43], v[48:49], v[26:27]
	v_cvt_pk_bf16_f32 v36, v36, v37
	v_cvt_pk_bf16_f32 v37, v38, v39
	v_mul_f32_e32 v31, v31, v31
	v_cvt_pk_bf16_f32 v38, v42, v43
	v_cvt_pk_bf16_f32 v39, v40, v41
	global_store_dwordx4 v[52:53], v[36:39], off
	global_load_dwordx4 v[36:39], v[54:55], off offset:512
	s_nop 0
	global_load_dwordx4 v[40:43], v[54:55], off offset:528
	global_load_dwordx4 v[44:47], v[134:135], off offset:512
	global_load_dwordx4 v[48:51], v[134:135], off offset:528
	v_mul_f32_e32 v33, v33, v33
	v_mul_f32_e32 v27, v27, v27
	v_fmac_f32_e32 v31, v30, v30
	v_fmac_f32_e32 v33, v32, v32
	v_mul_f32_e32 v29, v29, v29
	v_fmac_f32_e32 v27, v26, v26
	v_add_f32_e32 v26, v31, v33
	v_fmac_f32_e32 v29, v28, v28
	v_add_f32_e32 v26, v27, v26
	v_add_f32_e32 v26, v29, v26
	s_waitcnt vmcnt(3)
	v_pk_add_f32 v[24:25], v[24:25], v[38:39]
	v_pk_add_f32 v[22:23], v[22:23], v[36:37]
	s_waitcnt vmcnt(2)
	v_pk_add_f32 v[18:19], v[18:19], v[40:41]
	v_mul_f32_e32 v27, v23, v23
	v_mul_f32_e32 v28, v25, v25
	v_pk_add_f32 v[20:21], v[20:21], v[42:43]
	v_mul_f32_e32 v29, v19, v19
	v_fmac_f32_e32 v27, v22, v22
	v_fmac_f32_e32 v28, v24, v24
	v_mul_f32_e32 v30, v21, v21
	v_fmac_f32_e32 v29, v18, v18
	v_add_f32_e32 v27, v27, v28
	v_fmac_f32_e32 v30, v20, v20
	v_add_f32_e32 v27, v29, v27
	v_add_f32_e32 v27, v30, v27
	v_add_f32_e32 v30, v26, v27
	ds_bpermute_b32 v31, v122, v30
	global_store_dwordx4 v[54:55], v[22:25], off offset:512 nt
	global_store_dwordx4 v[54:55], v[18:21], off offset:528 nt
	s_waitcnt vmcnt(2)
	v_pk_mul_f32 v[28:29], v[48:49], v[18:19]
	v_pk_mul_f32 v[22:23], v[44:45], v[22:23]
	v_pk_mul_f32 v[24:25], v[46:47], v[24:25]
	s_waitcnt lgkmcnt(0)
	v_add_f32_e32 v18, v30, v31
	ds_bpermute_b32 v19, v116, v18
	v_pk_mul_f32 v[26:27], v[50:51], v[20:21]
	v_cvt_pk_bf16_f32 v20, v22, v23
	v_cvt_pk_bf16_f32 v21, v24, v25
	v_cvt_pk_bf16_f32 v22, v28, v29
	s_nop 0
	v_cvt_pk_bf16_f32 v23, v26, v27
	global_store_dwordx4 v[52:53], v[20:23], off offset:256
	s_and_saveexec_b64 s[42:43], s[0:1]
	s_cbranch_execz .LBB0_715
	v_lshlrev_b64 v[20:21], 8, v[34:35]
	v_lshl_add_u64 v[20:21], s[38:39], 0, v[20:21]
	v_lshl_add_u64 v[20:21], s[40:41], 2, v[20:21]
	s_lshl_b32 s10, s60, 2
	v_lshl_add_u64 v[20:21], v[20:21], 0, s[10:11]
	s_waitcnt lgkmcnt(0)
	v_add_f32_e32 v18, v18, v19
	global_store_dword v[20:21], v18, off
.LBB0_715:
	s_or_b64 exec, exec, s[42:43]
	v_add_u32_e32 v18, 0xb0, v138
	s_waitcnt lgkmcnt(0)
	v_ashrrev_i32_e32 v19, 31, v18
	v_lshlrev_b64 v[20:21], 12, v[18:19]
	v_lshl_add_u64 v[36:37], v[20:21], 0, v[136:137]
	v_lshl_add_u64 v[38:39], v[36:37], 2, s[26:27]
	global_load_dwordx4 v[20:23], v[38:39], off nt
	global_load_dwordx4 v[24:27], v[38:39], off offset:16 nt
	global_load_dwordx4 v[28:31], v[134:135], off
	global_load_dwordx4 v[32:35], v[134:135], off offset:16
	v_lshl_add_u64 v[36:37], v[36:37], 1, s[20:21]
	s_waitcnt vmcnt(3)
	v_pk_add_f32 v[16:17], v[16:17], v[22:23]
	v_pk_add_f32 v[14:15], v[14:15], v[20:21]
	s_waitcnt vmcnt(2)
	v_pk_add_f32 v[12:13], v[12:13], v[26:27]
	v_pk_add_f32 v[10:11], v[10:11], v[24:25]
	s_waitcnt vmcnt(1)
	v_pk_mul_f32 v[22:23], v[30:31], v[16:17]
	v_pk_mul_f32 v[20:21], v[28:29], v[14:15]
	global_store_dwordx4 v[38:39], v[14:17], off nt
	global_store_dwordx4 v[38:39], v[10:13], off offset:16 nt
	s_waitcnt vmcnt(2)
	v_pk_mul_f32 v[24:25], v[34:35], v[12:13]
	v_pk_mul_f32 v[26:27], v[32:33], v[10:11]
	v_cvt_pk_bf16_f32 v20, v20, v21
	v_cvt_pk_bf16_f32 v21, v22, v23
	v_mul_f32_e32 v15, v15, v15
	v_cvt_pk_bf16_f32 v22, v26, v27
	v_cvt_pk_bf16_f32 v23, v24, v25
	global_store_dwordx4 v[36:37], v[20:23], off
	global_load_dwordx4 v[20:23], v[38:39], off offset:512
	s_nop 0
	global_load_dwordx4 v[24:27], v[38:39], off offset:528
	global_load_dwordx4 v[28:31], v[134:135], off offset:512
	global_load_dwordx4 v[32:35], v[134:135], off offset:528
	v_mul_f32_e32 v17, v17, v17
	v_mul_f32_e32 v11, v11, v11
	v_fmac_f32_e32 v15, v14, v14
	v_fmac_f32_e32 v17, v16, v16
	v_mul_f32_e32 v13, v13, v13
	v_fmac_f32_e32 v11, v10, v10
	v_add_f32_e32 v10, v15, v17
	v_fmac_f32_e32 v13, v12, v12
	v_add_f32_e32 v10, v11, v10
	v_add_f32_e32 v10, v13, v10
	s_waitcnt vmcnt(3)
	v_pk_add_f32 v[8:9], v[8:9], v[22:23]
	v_pk_add_f32 v[6:7], v[6:7], v[20:21]
	s_waitcnt vmcnt(2)
	v_pk_add_f32 v[2:3], v[2:3], v[24:25]
	v_mul_f32_e32 v11, v7, v7
	v_mul_f32_e32 v12, v9, v9
	v_pk_add_f32 v[4:5], v[4:5], v[26:27]
	v_mul_f32_e32 v13, v3, v3
	v_fmac_f32_e32 v11, v6, v6
	v_fmac_f32_e32 v12, v8, v8
	v_mul_f32_e32 v14, v5, v5
	v_fmac_f32_e32 v13, v2, v2
	v_add_f32_e32 v11, v11, v12
	v_fmac_f32_e32 v14, v4, v4
	v_add_f32_e32 v11, v13, v11
	v_add_f32_e32 v11, v14, v11
	v_add_f32_e32 v14, v10, v11
	ds_bpermute_b32 v15, v122, v14
	global_store_dwordx4 v[38:39], v[6:9], off offset:512 nt
	global_store_dwordx4 v[38:39], v[2:5], off offset:528 nt
	s_waitcnt vmcnt(2)
	v_pk_mul_f32 v[12:13], v[32:33], v[2:3]
	v_pk_mul_f32 v[6:7], v[28:29], v[6:7]
	v_pk_mul_f32 v[8:9], v[30:31], v[8:9]
	s_waitcnt lgkmcnt(0)
	v_add_f32_e32 v2, v14, v15
	ds_bpermute_b32 v3, v116, v2
	v_pk_mul_f32 v[10:11], v[34:35], v[4:5]
	v_cvt_pk_bf16_f32 v4, v6, v7
	v_cvt_pk_bf16_f32 v5, v8, v9
	v_cvt_pk_bf16_f32 v6, v12, v13
	s_nop 0
	v_cvt_pk_bf16_f32 v7, v10, v11
	global_store_dwordx4 v[36:37], v[4:7], off offset:256
	s_and_saveexec_b64 s[42:43], s[0:1]
	s_cbranch_execz .LBB0_717
	v_lshlrev_b64 v[4:5], 8, v[18:19]
	v_lshl_add_u64 v[4:5], s[38:39], 0, v[4:5]
	v_lshl_add_u64 v[4:5], s[40:41], 2, v[4:5]
	s_lshl_b32 s10, s60, 2
	v_lshl_add_u64 v[4:5], v[4:5], 0, s[10:11]
	s_waitcnt lgkmcnt(0)
	v_add_f32_e32 v2, v2, v3
	global_store_dword v[4:5], v2, off

;     __host__ __device__ bool next(int i, Unit& u) const {
;         const long L = (long)i * G + c; if (L >= nwg) return false;
;         int wgid = (int)L; { const int q = nwg / NXCD, r = nwg % NXCD, xcd = wgid % NXCD, off = wgid / NXCD; wgid = (xcd < r ? xcd * (q + 1) : r * (q + 1) + (xcd - r) * q) + off; }
;         const int nig = WGM * nN, gid = wgid / nig, fm = gid * WGM, gsz = (nM - fm) < WGM ? (nM - fm) : WGM;
;         u.pm = fm + ((wgid % nig) % gsz); u.pn = (wgid % nig) / gsz; return true;
;     __device__ __forceinline__ void a_ready(const Unit& u) const {
;         if ((slot ? pm1 : pm0) == u.pm) return;
;         slot ^= 1; if (slot) pm1 = u.pm; else pm0 = u.pm;
;         const int t = threadIdx.x, row = t >> 1, part = t & 1;
;         const f32x4* p = (const f32x4*)(ssq + (size_t)(u.pm * BM + row) * 64 + part * 32);
;         float s = 0.f;
; #pragma unroll
;         for (int j = 0; j < 8; ++j) { const f32x4 v = p[j]; s += (v[0] + v[1]) + (v[2] + v[3]); }
;         s += __shfl_xor(s, 1);
;         if (part == 0) tab[slot * 256 + row] = 1.0f / sqrtf(s * inv_n + eps);
.LBB0_771:
	s_cmp_lt_i32 s30, 10
	s_cselect_b64 s[4:5], -1, 0
	s_and_b64 s[10:11], s[4:5], s[0:1]
	s_andn2_b64 vcc, exec, s[10:11]
	s_cbranch_vccnz .LBB0_801
	v_readfirstlane_b32 s3, v0
	s_cmpk_gt_i32 s2, 0xabf
	v_lshlrev_b32_e32 v1, 2, v0
	s_cbranch_scc1 .LBB0_794
	s_ashr_i32 s35, s2, 31
	s_lshr_b32 s0, s35, 29
	s_add_i32 s0, s2, s0
	s_ashr_i32 s1, s0, 3
	s_and_b32 s0, s0, -8
	s_sub_i32 s0, s2, s0
	s_cmp_lt_i32 s0, 0
	s_movk_i32 s4, 0x159
	s_cselect_b32 s4, s4, 0x158
	s_mul_i32 s0, s0, s4
	s_add_i32 s0, s0, s1
	s_mul_hi_i32 s1, s0, 0x2fa0be83
	s_lshr_b32 s4, s1, 31
	s_ashr_i32 s1, s1, 7
	s_add_i32 s1, s1, s4
	s_lshl_b32 s4, s1, 3
	s_mulk_i32 s1, 0x2b0
	s_sub_i32 s0, s0, s1
	s_sext_i32_i16 s1, s0
	s_bfe_u32 s1, s1, 0x3001c
	s_add_i32 s1, s0, s1
	s_sext_i32_i16 s6, s1
	s_and_b32 s1, s1, 0xfff8
	s_sub_i32 s0, s0, s1
	s_sext_i32_i16 s0, s0
	s_add_i32 s12, s4, s0
	v_lshrrev_b32_e32 v138, 1, v0
	s_mov_b32 s48, 0
	s_cmp_eq_u32 s12, -1
	v_and_b32_e32 v2, 1, v0
	s_cbranch_scc1 .LBB0_777
	v_lshl_or_b32 v4, s12, 8, v138
	v_ashrrev_i32_e32 v5, 31, v4
	v_lshlrev_b64 v[4:5], 8, v[4:5]
	v_lshl_add_u64 v[4:5], s[38:39], 0, v[4:5]
	v_lshlrev_b32_e32 v6, 7, v2
	v_mov_b32_e32 v7, 0
	v_lshl_add_u64 v[36:37], v[4:5], 0, v[6:7]
	global_load_dwordx4 v[4:7], v[36:37], off nt
	global_load_dwordx4 v[8:11], v[36:37], off offset:16 nt
	global_load_dwordx4 v[12:15], v[36:37], off offset:32 nt
	global_load_dwordx4 v[16:19], v[36:37], off offset:48 nt
	global_load_dwordx4 v[20:23], v[36:37], off offset:64 nt
	global_load_dwordx4 v[24:27], v[36:37], off offset:80 nt
	global_load_dwordx4 v[28:31], v[36:37], off offset:96 nt
	global_load_dwordx4 v[32:35], v[36:37], off offset:112 nt
	s_waitcnt lgkmcnt(0)
	v_mbcnt_lo_u32_b32 v3, -1, 0
	v_mbcnt_hi_u32_b32 v3, -1, v3
	v_and_b32_e32 v37, 64, v3
	v_xor_b32_e32 v36, 1, v3
	v_add_u32_e32 v37, 64, v37
	v_cmp_lt_i32_e32 vcc, v36, v37
	s_nop 1
	v_cndmask_b32_e32 v36, v3, v36, vcc
	v_cmp_eq_u32_e32 vcc, 0, v2
	s_waitcnt vmcnt(7)
	v_add_f32_e32 v3, v4, v5
	v_add_f32_e32 v4, v6, v7
	s_waitcnt vmcnt(6)
	v_add_f32_e32 v5, v8, v9
	v_add_f32_e32 v6, v10, v11
	v_add_f32_e32 v3, v3, v4
	s_waitcnt vmcnt(5)
	v_add_f32_e32 v7, v12, v13
	v_add_f32_e32 v8, v14, v15
	v_add_f32_e32 v4, v5, v6
	v_add_f32_e32 v3, 0, v3
	s_waitcnt vmcnt(4)
	v_add_f32_e32 v9, v16, v17
	v_add_f32_e32 v10, v18, v19
	v_add_f32_e32 v5, v7, v8
	v_add_f32_e32 v3, v3, v4
	s_waitcnt vmcnt(3)
	v_add_f32_e32 v11, v20, v21
	v_add_f32_e32 v12, v22, v23
	v_add_f32_e32 v6, v9, v10
	v_add_f32_e32 v3, v3, v5
	s_waitcnt vmcnt(2)
	v_add_f32_e32 v13, v24, v25
	v_add_f32_e32 v14, v26, v27
	v_add_f32_e32 v7, v11, v12
	v_add_f32_e32 v3, v3, v6
	s_waitcnt vmcnt(1)
	v_add_f32_e32 v15, v28, v29
	v_add_f32_e32 v16, v30, v31
	v_add_f32_e32 v8, v13, v14
	v_add_f32_e32 v3, v3, v7
	s_waitcnt vmcnt(0)
	v_add_f32_e32 v17, v32, v33
	v_add_f32_e32 v18, v34, v35
	v_add_f32_e32 v9, v15, v16
	v_add_f32_e32 v3, v3, v8
	v_add_f32_e32 v10, v17, v18
	v_add_f32_e32 v3, v3, v9
	v_add_f32_e32 v3, v3, v10
	v_lshlrev_b32_e32 v4, 2, v36
	ds_bpermute_b32 v4, v4, v3
	s_and_saveexec_b64 s[4:5], vcc
	s_cbranch_execz .LBB0_776
	s_waitcnt lgkmcnt(0)
	v_add_f32_e32 v3, v3, v4
	v_mov_b32_e32 v4, 0x358637bd
	v_fmac_f32_e32 v4, 0x39800000, v3
	s_mov_b32 s0, 0xf800000
	v_mul_f32_e32 v3, 0x4f800000, v4
	v_cmp_gt_f32_e32 vcc, s0, v4
	s_nop 1
	v_cndmask_b32_e32 v3, v4, v3, vcc
	v_sqrt_f32_e32 v4, v3
	s_nop 0
	v_add_u32_e32 v5, -1, v4
	v_fma_f32 v6, -v5, v4, v3
	v_cmp_ge_f32_e64 s[0:1], 0, v6
	v_add_u32_e32 v6, 1, v4
	s_nop 0
	v_cndmask_b32_e64 v5, v4, v5, s[0:1]
	v_fma_f32 v4, -v6, v4, v3
	v_cmp_lt_f32_e64 s[0:1], 0, v4
	s_nop 1
	v_cndmask_b32_e64 v4, v5, v6, s[0:1]
	v_mul_f32_e32 v5, 0x37800000, v4
	v_cndmask_b32_e32 v4, v4, v5, vcc
	v_mov_b32_e32 v5, 0x260
	v_cmp_class_f32_e32 vcc, v3, v5
	s_nop 1
	v_cndmask_b32_e32 v3, v4, v3, vcc
	v_div_scale_f32 v4, s[0:1], v3, v3, 1.0
	v_rcp_f32_e32 v5, v4
	s_nop 0
	v_fma_f32 v6, -v4, v5, 1.0
	v_fmac_f32_e32 v5, v6, v5
	v_div_scale_f32 v6, vcc, 1.0, v3, 1.0
	v_mul_f32_e32 v7, v6, v5
	v_fma_f32 v8, -v4, v7, v6
	v_fmac_f32_e32 v7, v8, v5
	v_fma_f32 v4, -v4, v7, v6
	v_div_fmas_f32 v4, v4, v5, v7
	v_div_fixup_f32 v3, v4, v3, 1.0
	v_lshl_add_u32 v4, v138, 2, 0
	v_add_u32_e32 v4, 0x20400, v4
	ds_write_b32 v4, v3

; __device__ __forceinline__ unsigned cvt_pk_bf16(float lo, float hi) { unsigned r; asm volatile("v_cvt_pk_bf16_f32 %0, %1, %2" : "=v"(r) : "v"(lo), "v"(hi)); return r; }
;     __device__ __forceinline__ void operator()(const f32x4 (&acc)[2][2][4][2], const Unit& u, int wr, int wc, int fr, int fq) const {
;     ...
;             for (int m = 0; m < 4; ++m) { const size_t off = (size_t)(row0 + ai * HALF + m * 16) * ldc + col0;
; #pragma unroll
;                 for (int bj = 0; bj < 2; ++bj) { const f32x4 b0 = *(const f32x4*)(base + off + bj * HALF), b1 = *(const f32x4*)(base + off + bj * HALF + 4);
;                     const f32x4 v0 = b0 + acc[ai][bj][m][0] * alpha, v1 = b1 + acc[ai][bj][m][1] * alpha;
;                     u32x4 w; w.x = cvt_pk_bf16(v0[0], v0[1]); w.y = cvt_pk_bf16(v0[2], v0[3]); w.z = cvt_pk_bf16(v1[0], v1[1]); w.w = cvt_pk_bf16(v1[2], v1[3]);
;                     *(u32x4*)(O + off + bj * HALF) = w; } }
.LBB0_876:
	v_lshl_add_u32 v138, s65, 8, v143
	v_lshl_or_b32 v136, s66, 8, v144
	v_ashrrev_i32_e32 v139, 31, v138
	v_ashrrev_i32_e32 v137, 31, v136
	v_lshlrev_b64 v[134:135], 12, v[138:139]
	v_lshl_add_u64 v[134:135], v[134:135], 0, v[136:137]
	v_lshl_add_u64 v[158:159], v[134:135], 2, s[26:27]
	global_load_dwordx4 v[150:153], v[158:159], off nt
	global_load_dwordx4 v[154:157], v[158:159], off offset:16 nt
	v_lshl_add_u64 v[160:161], v[134:135], 1, s[20:21]
	s_and_b64 vcc, exec, s[0:1]
	s_mov_b64 s[0:1], -1
	s_waitcnt vmcnt(1)
	v_pk_fma_f32 v[126:127], v[126:127], 0.5, v[150:151] op_sel_hi:[1,0,1]
	s_waitcnt vmcnt(0)
	v_pk_fma_f32 v[150:151], v[124:125], 0.5, v[156:157] op_sel_hi:[1,0,1]
	v_pk_fma_f32 v[124:125], v[122:123], 0.5, v[154:155] op_sel_hi:[1,0,1]
	v_pk_fma_f32 v[128:129], v[128:129], 0.5, v[152:153] op_sel_hi:[1,0,1]
	v_cvt_pk_bf16_f32 v122, v126, v127
	s_nop 0
	v_cvt_pk_bf16_f32 v123, v128, v129
	v_cvt_pk_bf16_f32 v124, v124, v125
	v_cvt_pk_bf16_f32 v125, v150, v151
	global_store_dwordx4 v[160:161], v[122:125], off
	global_load_dwordx4 v[122:125], v[158:159], off offset:512 nt
	s_nop 0
	global_load_dwordx4 v[126:129], v[158:159], off offset:528 nt
	v_or_b32_e32 v150, 16, v138
	v_ashrrev_i32_e32 v151, 31, v150
	v_lshlrev_b64 v[150:151], 12, v[150:151]
	v_lshl_add_u64 v[150:151], v[150:151], 0, v[136:137]
	v_lshl_add_u64 v[152:153], v[150:151], 2, s[26:27]
	s_waitcnt vmcnt(1)
	v_pk_fma_f32 v[118:119], v[118:119], 0.5, v[122:123] op_sel_hi:[1,0,1]
	s_waitcnt vmcnt(0)
	v_pk_fma_f32 v[122:123], v[116:117], 0.5, v[128:129] op_sel_hi:[1,0,1]
	v_pk_fma_f32 v[116:117], v[114:115], 0.5, v[126:127] op_sel_hi:[1,0,1]
	v_pk_fma_f32 v[120:121], v[120:121], 0.5, v[124:125] op_sel_hi:[1,0,1]
	v_cvt_pk_bf16_f32 v114, v118, v119
	s_nop 0
	v_cvt_pk_bf16_f32 v115, v120, v121
	v_cvt_pk_bf16_f32 v116, v116, v117
	v_cvt_pk_bf16_f32 v117, v122, v123
	global_store_dwordx4 v[160:161], v[114:117], off offset:256
	global_load_dwordx4 v[114:117], v[152:153], off nt
	s_nop 0
	global_load_dwordx4 v[118:121], v[152:153], off offset:16 nt
	v_lshl_add_u64 v[122:123], v[150:151], 1, s[20:21]
	s_waitcnt vmcnt(1)
	v_pk_fma_f32 v[110:111], v[110:111], 0.5, v[114:115] op_sel_hi:[1,0,1]
	s_waitcnt vmcnt(0)
	v_pk_fma_f32 v[114:115], v[108:109], 0.5, v[120:121] op_sel_hi:[1,0,1]
	v_pk_fma_f32 v[108:109], v[106:107], 0.5, v[118:119] op_sel_hi:[1,0,1]
	v_pk_fma_f32 v[112:113], v[112:113], 0.5, v[116:117] op_sel_hi:[1,0,1]
	v_cvt_pk_bf16_f32 v106, v110, v111
	s_nop 0
	v_cvt_pk_bf16_f32 v107, v112, v113
	v_cvt_pk_bf16_f32 v108, v108, v109
	v_cvt_pk_bf16_f32 v109, v114, v115
	global_store_dwordx4 v[122:123], v[106:109], off
	global_load_dwordx4 v[106:109], v[152:153], off offset:512 nt
	s_nop 0
	global_load_dwordx4 v[110:113], v[152:153], off offset:528 nt
	v_or_b32_e32 v114, 32, v138
	v_ashrrev_i32_e32 v115, 31, v114
	v_lshlrev_b64 v[114:115], 12, v[114:115]
	v_lshl_add_u64 v[114:115], v[114:115], 0, v[136:137]
	v_lshl_add_u64 v[116:117], v[114:115], 2, s[26:27]
	s_waitcnt vmcnt(1)
	v_pk_fma_f32 v[102:103], v[102:103], 0.5, v[106:107] op_sel_hi:[1,0,1]
	s_waitcnt vmcnt(0)
	v_pk_fma_f32 v[106:107], v[100:101], 0.5, v[112:113] op_sel_hi:[1,0,1]
	v_pk_fma_f32 v[100:101], v[98:99], 0.5, v[110:111] op_sel_hi:[1,0,1]
	v_pk_fma_f32 v[104:105], v[104:105], 0.5, v[108:109] op_sel_hi:[1,0,1]
	v_cvt_pk_bf16_f32 v98, v102, v103
	s_nop 0
	v_cvt_pk_bf16_f32 v99, v104, v105
	v_cvt_pk_bf16_f32 v100, v100, v101
	v_cvt_pk_bf16_f32 v101, v106, v107
	global_store_dwordx4 v[122:123], v[98:101], off offset:256
	global_load_dwordx4 v[98:101], v[116:117], off nt
	s_nop 0
	global_load_dwordx4 v[102:105], v[116:117], off offset:16 nt
	v_lshl_add_u64 v[106:107], v[114:115], 1, s[20:21]
	s_waitcnt vmcnt(1)
	v_pk_fma_f32 v[94:95], v[94:95], 0.5, v[98:99] op_sel_hi:[1,0,1]
	s_waitcnt vmcnt(0)
	v_pk_fma_f32 v[98:99], v[92:93], 0.5, v[104:105] op_sel_hi:[1,0,1]
	v_pk_fma_f32 v[92:93], v[90:91], 0.5, v[102:103] op_sel_hi:[1,0,1]
	v_pk_fma_f32 v[96:97], v[96:97], 0.5, v[100:101] op_sel_hi:[1,0,1]
	v_cvt_pk_bf16_f32 v90, v94, v95
	s_nop 0
	v_cvt_pk_bf16_f32 v91, v96, v97
	v_cvt_pk_bf16_f32 v92, v92, v93
	v_cvt_pk_bf16_f32 v93, v98, v99
	global_store_dwordx4 v[106:107], v[90:93], off
	global_load_dwordx4 v[90:93], v[116:117], off offset:512 nt
	s_nop 0
	global_load_dwordx4 v[94:97], v[116:117], off offset:528 nt
	v_or_b32_e32 v98, 48, v138
	v_ashrrev_i32_e32 v99, 31, v98
	v_lshlrev_b64 v[98:99], 12, v[98:99]
	v_lshl_add_u64 v[98:99], v[98:99], 0, v[136:137]
	v_lshl_add_u64 v[100:101], v[98:99], 2, s[26:27]
	s_waitcnt vmcnt(1)
	v_pk_fma_f32 v[86:87], v[86:87], 0.5, v[90:91] op_sel_hi:[1,0,1]
	s_waitcnt vmcnt(0)
	v_pk_fma_f32 v[90:91], v[84:85], 0.5, v[96:97] op_sel_hi:[1,0,1]
	v_pk_fma_f32 v[84:85], v[82:83], 0.5, v[94:95] op_sel_hi:[1,0,1]
	v_pk_fma_f32 v[88:89], v[88:89], 0.5, v[92:93] op_sel_hi:[1,0,1]
	v_cvt_pk_bf16_f32 v82, v86, v87
	s_nop 0
	v_cvt_pk_bf16_f32 v83, v88, v89
	v_cvt_pk_bf16_f32 v84, v84, v85
	v_cvt_pk_bf16_f32 v85, v90, v91
	global_store_dwordx4 v[106:107], v[82:85], off offset:256
	global_load_dwordx4 v[82:85], v[100:101], off nt
	s_nop 0
	global_load_dwordx4 v[86:89], v[100:101], off offset:16 nt
	v_lshl_add_u64 v[90:91], v[98:99], 1, s[20:21]
	s_waitcnt vmcnt(1)
	v_pk_fma_f32 v[78:79], v[78:79], 0.5, v[82:83] op_sel_hi:[1,0,1]
	s_waitcnt vmcnt(0)
	v_pk_fma_f32 v[82:83], v[76:77], 0.5, v[88:89] op_sel_hi:[1,0,1]
	v_pk_fma_f32 v[76:77], v[74:75], 0.5, v[86:87] op_sel_hi:[1,0,1]
	v_pk_fma_f32 v[80:81], v[80:81], 0.5, v[84:85] op_sel_hi:[1,0,1]
	v_cvt_pk_bf16_f32 v74, v78, v79
	s_nop 0
	v_cvt_pk_bf16_f32 v75, v80, v81
	v_cvt_pk_bf16_f32 v76, v76, v77
	v_cvt_pk_bf16_f32 v77, v82, v83
	global_store_dwordx4 v[90:91], v[74:77], off
	global_load_dwordx4 v[74:77], v[100:101], off offset:512 nt
	s_nop 0
	global_load_dwordx4 v[78:81], v[100:101], off offset:528 nt
	v_lshl_add_u64 v[82:83], v[134:135], 0, s[12:13]
	v_lshl_add_u64 v[84:85], v[82:83], 2, s[26:27]
	s_waitcnt vmcnt(1)
; __device__ __forceinline__ unsigned cvt_pk_bf16(float lo, float hi) { unsigned r; asm volatile("v_cvt_pk_bf16_f32 %0, %1, %2" : "=v"(r) : "v"(lo), "v"(hi)); return r; }
;     __device__ __forceinline__ void operator()(const f32x4 (&acc)[2][2][4][2], const Unit& u, int wr, int wc, int fr, int fq) const {
;     ...
;             for (int m = 0; m < 4; ++m) { const size_t off = (size_t)(row0 + ai * HALF + m * 16) * ldc + col0;
; #pragma unroll
;                 for (int bj = 0; bj < 2; ++bj) { const f32x4 b0 = *(const f32x4*)(base + off + bj * HALF), b1 = *(const f32x4*)(base + off + bj * HALF + 4);
;                     const f32x4 v0 = b0 + acc[ai][bj][m][0] * alpha, v1 = b1 + acc[ai][bj][m][1] * alpha;
;                     u32x4 w; w.x = cvt_pk_bf16(v0[0], v0[1]); w.y = cvt_pk_bf16(v0[2], v0[3]); w.z = cvt_pk_bf16(v1[0], v1[1]); w.w = cvt_pk_bf16(v1[2], v1[3]);
;                     *(u32x4*)(O + off + bj * HALF) = w; } }
	v_pk_fma_f32 v[70:71], v[70:71], 0.5, v[74:75] op_sel_hi:[1,0,1]
	s_waitcnt vmcnt(0)
	v_pk_fma_f32 v[74:75], v[68:69], 0.5, v[80:81] op_sel_hi:[1,0,1]
	v_pk_fma_f32 v[68:69], v[66:67], 0.5, v[78:79] op_sel_hi:[1,0,1]
	v_pk_fma_f32 v[72:73], v[72:73], 0.5, v[76:77] op_sel_hi:[1,0,1]
	v_cvt_pk_bf16_f32 v66, v70, v71
	s_nop 0
	v_cvt_pk_bf16_f32 v67, v72, v73
	v_cvt_pk_bf16_f32 v68, v68, v69
	v_cvt_pk_bf16_f32 v69, v74, v75
	global_store_dwordx4 v[90:91], v[66:69], off offset:256
	global_load_dwordx4 v[66:69], v[84:85], off nt
	s_nop 0
	global_load_dwordx4 v[70:73], v[84:85], off offset:16 nt
	v_lshl_add_u64 v[74:75], v[82:83], 1, s[20:21]
	s_waitcnt vmcnt(1)
	v_pk_fma_f32 v[62:63], v[62:63], 0.5, v[66:67] op_sel_hi:[1,0,1]
	s_waitcnt vmcnt(0)
	v_pk_fma_f32 v[66:67], v[60:61], 0.5, v[72:73] op_sel_hi:[1,0,1]
	v_pk_fma_f32 v[60:61], v[58:59], 0.5, v[70:71] op_sel_hi:[1,0,1]
	v_pk_fma_f32 v[64:65], v[64:65], 0.5, v[68:69] op_sel_hi:[1,0,1]
	v_cvt_pk_bf16_f32 v58, v62, v63
	s_nop 0
	v_cvt_pk_bf16_f32 v59, v64, v65
	v_cvt_pk_bf16_f32 v60, v60, v61
	v_cvt_pk_bf16_f32 v61, v66, v67
	global_store_dwordx4 v[74:75], v[58:61], off
	global_load_dwordx4 v[58:61], v[84:85], off offset:512 nt
	s_nop 0
	global_load_dwordx4 v[62:65], v[84:85], off offset:528 nt
	v_lshl_add_u64 v[66:67], v[134:135], 0, s[14:15]
	v_lshl_add_u64 v[68:69], v[66:67], 2, s[26:27]
	s_waitcnt vmcnt(1)
	v_pk_fma_f32 v[54:55], v[54:55], 0.5, v[58:59] op_sel_hi:[1,0,1]
	s_waitcnt vmcnt(0)
	v_pk_fma_f32 v[58:59], v[52:53], 0.5, v[64:65] op_sel_hi:[1,0,1]
	v_pk_fma_f32 v[52:53], v[50:51], 0.5, v[62:63] op_sel_hi:[1,0,1]
	v_pk_fma_f32 v[56:57], v[56:57], 0.5, v[60:61] op_sel_hi:[1,0,1]
	v_cvt_pk_bf16_f32 v50, v54, v55
	s_nop 0
	v_cvt_pk_bf16_f32 v51, v56, v57
	v_cvt_pk_bf16_f32 v52, v52, v53
	v_cvt_pk_bf16_f32 v53, v58, v59
	global_store_dwordx4 v[74:75], v[50:53], off offset:256
	global_load_dwordx4 v[50:53], v[68:69], off nt
	s_nop 0
	global_load_dwordx4 v[54:57], v[68:69], off offset:16 nt
	v_lshl_add_u64 v[58:59], v[66:67], 1, s[20:21]
	s_waitcnt vmcnt(1)
	v_pk_fma_f32 v[46:47], v[46:47], 0.5, v[50:51] op_sel_hi:[1,0,1]
	s_waitcnt vmcnt(0)
	v_pk_fma_f32 v[50:51], v[44:45], 0.5, v[56:57] op_sel_hi:[1,0,1]
	v_pk_fma_f32 v[44:45], v[42:43], 0.5, v[54:55] op_sel_hi:[1,0,1]
	v_pk_fma_f32 v[48:49], v[48:49], 0.5, v[52:53] op_sel_hi:[1,0,1]
	v_cvt_pk_bf16_f32 v42, v46, v47
	s_nop 0
	v_cvt_pk_bf16_f32 v43, v48, v49
	v_cvt_pk_bf16_f32 v44, v44, v45
	v_cvt_pk_bf16_f32 v45, v50, v51
	global_store_dwordx4 v[58:59], v[42:45], off
	global_load_dwordx4 v[42:45], v[68:69], off offset:512 nt
	s_nop 0
	global_load_dwordx4 v[46:49], v[68:69], off offset:528 nt
	v_lshl_add_u64 v[50:51], v[134:135], 0, s[16:17]
	v_lshl_add_u64 v[52:53], v[50:51], 2, s[26:27]
	s_waitcnt vmcnt(1)
	v_pk_fma_f32 v[38:39], v[38:39], 0.5, v[42:43] op_sel_hi:[1,0,1]
	s_waitcnt vmcnt(0)
	v_pk_fma_f32 v[42:43], v[36:37], 0.5, v[48:49] op_sel_hi:[1,0,1]
	v_pk_fma_f32 v[36:37], v[34:35], 0.5, v[46:47] op_sel_hi:[1,0,1]
	v_pk_fma_f32 v[40:41], v[40:41], 0.5, v[44:45] op_sel_hi:[1,0,1]
	v_cvt_pk_bf16_f32 v34, v38, v39
	s_nop 0
	v_cvt_pk_bf16_f32 v35, v40, v41
	v_cvt_pk_bf16_f32 v36, v36, v37
	v_cvt_pk_bf16_f32 v37, v42, v43
	global_store_dwordx4 v[58:59], v[34:37], off offset:256
	global_load_dwordx4 v[34:37], v[52:53], off nt
	s_nop 0
	global_load_dwordx4 v[38:41], v[52:53], off offset:16 nt
	v_lshl_add_u64 v[42:43], v[50:51], 1, s[20:21]
	s_waitcnt vmcnt(1)
	v_pk_fma_f32 v[30:31], v[30:31], 0.5, v[34:35] op_sel_hi:[1,0,1]
	s_waitcnt vmcnt(0)
	v_pk_fma_f32 v[34:35], v[28:29], 0.5, v[40:41] op_sel_hi:[1,0,1]
	v_pk_fma_f32 v[28:29], v[26:27], 0.5, v[38:39] op_sel_hi:[1,0,1]
	v_pk_fma_f32 v[32:33], v[32:33], 0.5, v[36:37] op_sel_hi:[1,0,1]
	v_cvt_pk_bf16_f32 v26, v30, v31
	s_nop 0
	v_cvt_pk_bf16_f32 v27, v32, v33
	v_cvt_pk_bf16_f32 v28, v28, v29
	v_cvt_pk_bf16_f32 v29, v34, v35
	global_store_dwordx4 v[42:43], v[26:29], off
	global_load_dwordx4 v[26:29], v[52:53], off offset:512 nt
	s_nop 0
	global_load_dwordx4 v[30:33], v[52:53], off offset:528 nt
	v_lshl_add_u64 v[34:35], v[134:135], 0, s[18:19]
	v_lshl_add_u64 v[36:37], v[34:35], 2, s[26:27]
	s_waitcnt vmcnt(1)
	v_pk_fma_f32 v[22:23], v[22:23], 0.5, v[26:27] op_sel_hi:[1,0,1]
	s_waitcnt vmcnt(0)
	v_pk_fma_f32 v[26:27], v[20:21], 0.5, v[32:33] op_sel_hi:[1,0,1]
	v_pk_fma_f32 v[20:21], v[18:19], 0.5, v[30:31] op_sel_hi:[1,0,1]
	v_pk_fma_f32 v[24:25], v[24:25], 0.5, v[28:29] op_sel_hi:[1,0,1]
	v_cvt_pk_bf16_f32 v18, v22, v23
	s_nop 0
	v_cvt_pk_bf16_f32 v19, v24, v25
	v_cvt_pk_bf16_f32 v20, v20, v21
	v_cvt_pk_bf16_f32 v21, v26, v27
	global_store_dwordx4 v[42:43], v[18:21], off offset:256
	global_load_dwordx4 v[18:21], v[36:37], off nt
	s_nop 0
	global_load_dwordx4 v[22:25], v[36:37], off offset:16 nt
	v_lshl_add_u64 v[26:27], v[34:35], 1, s[20:21]
	s_waitcnt vmcnt(1)
	v_pk_fma_f32 v[14:15], v[14:15], 0.5, v[18:19] op_sel_hi:[1,0,1]
	s_waitcnt vmcnt(0)
	v_pk_fma_f32 v[18:19], v[12:13], 0.5, v[24:25] op_sel_hi:[1,0,1]
	v_pk_fma_f32 v[12:13], v[10:11], 0.5, v[22:23] op_sel_hi:[1,0,1]
	v_pk_fma_f32 v[16:17], v[16:17], 0.5, v[20:21] op_sel_hi:[1,0,1]
	v_cvt_pk_bf16_f32 v10, v14, v15
	s_nop 0
	v_cvt_pk_bf16_f32 v11, v16, v17
	v_cvt_pk_bf16_f32 v12, v12, v13
	v_cvt_pk_bf16_f32 v13, v18, v19
	global_store_dwordx4 v[26:27], v[10:13], off
	global_load_dwordx4 v[10:13], v[36:37], off offset:512 nt
	s_nop 0
	global_load_dwordx4 v[14:17], v[36:37], off offset:528 nt
	s_waitcnt vmcnt(1)
	v_pk_fma_f32 v[6:7], v[6:7], 0.5, v[10:11] op_sel_hi:[1,0,1]
	s_waitcnt vmcnt(0)
	v_pk_fma_f32 v[10:11], v[4:5], 0.5, v[16:17] op_sel_hi:[1,0,1]
	v_pk_fma_f32 v[4:5], v[2:3], 0.5, v[14:15] op_sel_hi:[1,0,1]
	v_pk_fma_f32 v[8:9], v[8:9], 0.5, v[12:13] op_sel_hi:[1,0,1]
	v_cvt_pk_bf16_f32 v2, v6, v7
	s_nop 0
	v_cvt_pk_bf16_f32 v3, v8, v9
	v_cvt_pk_bf16_f32 v4, v4, v5
	v_cvt_pk_bf16_f32 v5, v10, v11
	global_store_dwordx4 v[26:27], v[2:5], off offset:256
	s_cbranch_vccnz .LBB0_861
	s_andn2_b64 vcc, exec, s[8:9]
	s_cbranch_vccnz .LBB0_860
	s_barrier
	s_branch .LBB0_860
